# GEMM tile headers: accumulators zeroed once per tile (the zero-trip path's copy of the zeroing moved out of line)
# speedup vs baseline: 1.0081x; 1.0004x over previous
.Lzt_0:
	v_mov_b32_e32 v128, v129
	v_mov_b32_e32 v127, v129
	v_mov_b32_e32 v126, v129
	v_mov_b32_e32 v125, v129
	v_mov_b32_e32 v124, v129
	v_mov_b32_e32 v123, v129
	v_mov_b32_e32 v122, v129
	v_mov_b32_e32 v113, v129
	v_mov_b32_e32 v112, v129
	v_mov_b32_e32 v111, v129
	v_mov_b32_e32 v110, v129
	v_mov_b32_e32 v109, v129
	v_mov_b32_e32 v108, v129
	v_mov_b32_e32 v107, v129
	v_mov_b32_e32 v106, v129
	v_mov_b32_e32 v97, v129
	v_mov_b32_e32 v96, v129
	v_mov_b32_e32 v95, v129
	v_mov_b32_e32 v94, v129
	v_mov_b32_e32 v93, v129
	v_mov_b32_e32 v92, v129
	v_mov_b32_e32 v91, v129
	v_mov_b32_e32 v90, v129
	v_mov_b32_e32 v81, v129
	v_mov_b32_e32 v80, v129
	v_mov_b32_e32 v79, v129
	v_mov_b32_e32 v78, v129
	v_mov_b32_e32 v77, v129
	v_mov_b32_e32 v76, v129
	v_mov_b32_e32 v75, v129
	v_mov_b32_e32 v74, v129
	v_mov_b32_e32 v121, v129
	v_mov_b32_e32 v120, v129
	v_mov_b32_e32 v119, v129
	v_mov_b32_e32 v118, v129
	v_mov_b32_e32 v117, v129
	v_mov_b32_e32 v116, v129
	v_mov_b32_e32 v115, v129
	v_mov_b32_e32 v114, v129
	v_mov_b32_e32 v105, v129
	v_mov_b32_e32 v104, v129
	v_mov_b32_e32 v103, v129
	v_mov_b32_e32 v102, v129
	v_mov_b32_e32 v101, v129
	v_mov_b32_e32 v100, v129
	v_mov_b32_e32 v99, v129
	v_mov_b32_e32 v98, v129
	v_mov_b32_e32 v89, v129
	v_mov_b32_e32 v88, v129
	v_mov_b32_e32 v87, v129
	v_mov_b32_e32 v86, v129
	v_mov_b32_e32 v85, v129
	v_mov_b32_e32 v84, v129
	v_mov_b32_e32 v83, v129
	v_mov_b32_e32 v82, v129
	v_mov_b32_e32 v73, v129
	v_mov_b32_e32 v72, v129
	v_mov_b32_e32 v71, v129
	v_mov_b32_e32 v70, v129
	v_mov_b32_e32 v69, v129
	v_mov_b32_e32 v68, v129
	v_mov_b32_e32 v67, v129
	v_mov_b32_e32 v66, v129
	v_mov_b32_e32 v65, v129
	v_mov_b32_e32 v64, v129
	v_mov_b32_e32 v63, v129
	v_mov_b32_e32 v62, v129
	v_mov_b32_e32 v61, v129
	v_mov_b32_e32 v60, v129
	v_mov_b32_e32 v59, v129
	v_mov_b32_e32 v58, v129
	v_mov_b32_e32 v49, v129
	v_mov_b32_e32 v48, v129
	v_mov_b32_e32 v47, v129
	v_mov_b32_e32 v46, v129
	v_mov_b32_e32 v45, v129
	v_mov_b32_e32 v44, v129
	v_mov_b32_e32 v43, v129
	v_mov_b32_e32 v42, v129
	v_mov_b32_e32 v33, v129
	v_mov_b32_e32 v32, v129
	v_mov_b32_e32 v31, v129
	v_mov_b32_e32 v30, v129
	v_mov_b32_e32 v29, v129
	v_mov_b32_e32 v28, v129
	v_mov_b32_e32 v27, v129
	v_mov_b32_e32 v26, v129
	v_mov_b32_e32 v17, v129
	v_mov_b32_e32 v16, v129
	v_mov_b32_e32 v15, v129
	v_mov_b32_e32 v14, v129
	v_mov_b32_e32 v13, v129
	v_mov_b32_e32 v12, v129
	v_mov_b32_e32 v11, v129
	v_mov_b32_e32 v10, v129
	v_mov_b32_e32 v57, v129
	v_mov_b32_e32 v56, v129
	v_mov_b32_e32 v55, v129
	v_mov_b32_e32 v54, v129
	v_mov_b32_e32 v53, v129
	v_mov_b32_e32 v52, v129
	v_mov_b32_e32 v51, v129
	v_mov_b32_e32 v50, v129
	v_mov_b32_e32 v41, v129
	v_mov_b32_e32 v40, v129
	v_mov_b32_e32 v39, v129
	v_mov_b32_e32 v38, v129
	v_mov_b32_e32 v37, v129
	v_mov_b32_e32 v36, v129
	v_mov_b32_e32 v35, v129
	v_mov_b32_e32 v34, v129
	v_mov_b32_e32 v25, v129
	v_mov_b32_e32 v24, v129
	v_mov_b32_e32 v23, v129
	v_mov_b32_e32 v22, v129
	v_mov_b32_e32 v21, v129
	v_mov_b32_e32 v20, v129
	v_mov_b32_e32 v19, v129
	v_mov_b32_e32 v18, v129
	v_mov_b32_e32 v9, v129
	v_mov_b32_e32 v8, v129
	v_mov_b32_e32 v7, v129
	v_mov_b32_e32 v6, v129
	v_mov_b32_e32 v5, v129
	v_mov_b32_e32 v4, v129
	v_mov_b32_e32 v3, v129
	v_mov_b32_e32 v2, v129
	s_branch .LBB0_138

.LBB0_149:
	v_mov_b32_e32 v129, 0
	s_andn2_b64 vcc, exec, s[4:5]
	s_waitcnt vmcnt(0)
	s_cbranch_vccnz .Lzt_0
	s_add_u32 s41, s6, 0x100
	s_addc_u32 s42, s7, 0
	s_add_u32 s6, s8, 0xc000
	v_mov_b32_e32 v2, 0
	s_addc_u32 s7, s9, 0
	s_mov_b32 s8, 0
	v_mov_b32_e32 v3, v2
	v_mov_b32_e32 v4, v2
	v_mov_b32_e32 v5, v2
	v_mov_b32_e32 v6, v2
	v_mov_b32_e32 v7, v2
	v_mov_b32_e32 v8, v2
	v_mov_b32_e32 v9, v2
	v_mov_b32_e32 v18, v2
	v_mov_b32_e32 v19, v2
	v_mov_b32_e32 v20, v2
	v_mov_b32_e32 v21, v2
	v_mov_b32_e32 v22, v2
	v_mov_b32_e32 v23, v2
	v_mov_b32_e32 v24, v2
	v_mov_b32_e32 v25, v2
	v_mov_b32_e32 v34, v2
	v_mov_b32_e32 v35, v2
	v_mov_b32_e32 v36, v2
	v_mov_b32_e32 v37, v2
	v_mov_b32_e32 v38, v2
	v_mov_b32_e32 v39, v2
	v_mov_b32_e32 v40, v2
	v_mov_b32_e32 v41, v2
	v_mov_b32_e32 v50, v2
	v_mov_b32_e32 v51, v2
	v_mov_b32_e32 v52, v2
	v_mov_b32_e32 v53, v2
	v_mov_b32_e32 v54, v2
	v_mov_b32_e32 v55, v2
	v_mov_b32_e32 v56, v2
	v_mov_b32_e32 v57, v2
	v_mov_b32_e32 v10, v2
	v_mov_b32_e32 v11, v2
	v_mov_b32_e32 v12, v2
	v_mov_b32_e32 v13, v2
	v_mov_b32_e32 v14, v2
	v_mov_b32_e32 v15, v2
	v_mov_b32_e32 v16, v2
	v_mov_b32_e32 v17, v2
	v_mov_b32_e32 v26, v2
	v_mov_b32_e32 v27, v2
	v_mov_b32_e32 v28, v2
	v_mov_b32_e32 v29, v2
	v_mov_b32_e32 v30, v2
	v_mov_b32_e32 v31, v2
	v_mov_b32_e32 v32, v2
	v_mov_b32_e32 v33, v2
	v_mov_b32_e32 v42, v2
	v_mov_b32_e32 v43, v2
	v_mov_b32_e32 v44, v2
	v_mov_b32_e32 v45, v2
	v_mov_b32_e32 v46, v2
	v_mov_b32_e32 v47, v2
	v_mov_b32_e32 v48, v2
	v_mov_b32_e32 v49, v2
	v_mov_b32_e32 v58, v2
	v_mov_b32_e32 v59, v2
	v_mov_b32_e32 v60, v2
	v_mov_b32_e32 v61, v2
	v_mov_b32_e32 v62, v2
	v_mov_b32_e32 v63, v2
	v_mov_b32_e32 v64, v2
	v_mov_b32_e32 v65, v2
	v_mov_b32_e32 v66, v2
	v_mov_b32_e32 v67, v2
	v_mov_b32_e32 v68, v2
	v_mov_b32_e32 v69, v2
	v_mov_b32_e32 v70, v2
	v_mov_b32_e32 v71, v2
	v_mov_b32_e32 v72, v2
	v_mov_b32_e32 v73, v2
	v_mov_b32_e32 v82, v2
	v_mov_b32_e32 v83, v2
	v_mov_b32_e32 v84, v2
	v_mov_b32_e32 v85, v2
	v_mov_b32_e32 v86, v2
	v_mov_b32_e32 v87, v2
	v_mov_b32_e32 v88, v2
	v_mov_b32_e32 v89, v2
	v_mov_b32_e32 v98, v2
	v_mov_b32_e32 v99, v2
	v_mov_b32_e32 v100, v2
	v_mov_b32_e32 v101, v2
	v_mov_b32_e32 v102, v2
	v_mov_b32_e32 v103, v2
	v_mov_b32_e32 v104, v2
	v_mov_b32_e32 v105, v2
	v_mov_b32_e32 v114, v2
	v_mov_b32_e32 v115, v2
	v_mov_b32_e32 v116, v2
	v_mov_b32_e32 v117, v2
	v_mov_b32_e32 v118, v2
	v_mov_b32_e32 v119, v2
	v_mov_b32_e32 v120, v2
	v_mov_b32_e32 v121, v2
	v_mov_b32_e32 v74, v2
	v_mov_b32_e32 v75, v2
	v_mov_b32_e32 v76, v2
	v_mov_b32_e32 v77, v2
	v_mov_b32_e32 v78, v2
	v_mov_b32_e32 v79, v2
	v_mov_b32_e32 v80, v2
	v_mov_b32_e32 v81, v2
	v_mov_b32_e32 v90, v2
	v_mov_b32_e32 v91, v2
	v_mov_b32_e32 v92, v2
	v_mov_b32_e32 v93, v2
	v_mov_b32_e32 v94, v2
	v_mov_b32_e32 v95, v2
	v_mov_b32_e32 v96, v2
	v_mov_b32_e32 v97, v2
	v_mov_b32_e32 v106, v2
	v_mov_b32_e32 v107, v2
	v_mov_b32_e32 v108, v2
	v_mov_b32_e32 v109, v2
	v_mov_b32_e32 v110, v2
	v_mov_b32_e32 v111, v2
	v_mov_b32_e32 v112, v2
	v_mov_b32_e32 v113, v2
	v_mov_b32_e32 v122, v2
	v_mov_b32_e32 v123, v2
	v_mov_b32_e32 v124, v2
	v_mov_b32_e32 v125, v2
	v_mov_b32_e32 v126, v2
	v_mov_b32_e32 v127, v2
	v_mov_b32_e32 v128, v2
	v_mov_b32_e32 v129, v2

.Lzt_2:
	v_mov_b32_e32 v140, v141
	v_mov_b32_e32 v139, v141
	v_mov_b32_e32 v138, v141
	v_mov_b32_e32 v137, v141
	v_mov_b32_e32 v136, v141
	v_mov_b32_e32 v135, v141
	v_mov_b32_e32 v134, v141
	v_mov_b32_e32 v129, v141
	v_mov_b32_e32 v128, v141
	v_mov_b32_e32 v127, v141
	v_mov_b32_e32 v126, v141
	v_mov_b32_e32 v121, v141
	v_mov_b32_e32 v120, v141
	v_mov_b32_e32 v119, v141
	v_mov_b32_e32 v118, v141
	v_mov_b32_e32 v113, v141
	v_mov_b32_e32 v112, v141
	v_mov_b32_e32 v111, v141
	v_mov_b32_e32 v110, v141
	v_mov_b32_e32 v97, v141
	v_mov_b32_e32 v96, v141
	v_mov_b32_e32 v95, v141
	v_mov_b32_e32 v94, v141
	v_mov_b32_e32 v81, v141
	v_mov_b32_e32 v80, v141
	v_mov_b32_e32 v79, v141
	v_mov_b32_e32 v78, v141
	v_mov_b32_e32 v73, v141
	v_mov_b32_e32 v72, v141
	v_mov_b32_e32 v71, v141
	v_mov_b32_e32 v70, v141
	v_mov_b32_e32 v145, v141
	v_mov_b32_e32 v144, v141
	v_mov_b32_e32 v143, v141
	v_mov_b32_e32 v142, v141
	v_mov_b32_e32 v133, v141
	v_mov_b32_e32 v132, v141
	v_mov_b32_e32 v131, v141
	v_mov_b32_e32 v130, v141
	v_mov_b32_e32 v125, v141
	v_mov_b32_e32 v124, v141
	v_mov_b32_e32 v123, v141
	v_mov_b32_e32 v122, v141
	v_mov_b32_e32 v117, v141
	v_mov_b32_e32 v116, v141
	v_mov_b32_e32 v115, v141
	v_mov_b32_e32 v114, v141
	v_mov_b32_e32 v109, v141
	v_mov_b32_e32 v108, v141
	v_mov_b32_e32 v107, v141
	v_mov_b32_e32 v106, v141
	v_mov_b32_e32 v93, v141
	v_mov_b32_e32 v92, v141
	v_mov_b32_e32 v91, v141
	v_mov_b32_e32 v90, v141
	v_mov_b32_e32 v77, v141
	v_mov_b32_e32 v76, v141
	v_mov_b32_e32 v75, v141
	v_mov_b32_e32 v74, v141
	v_mov_b32_e32 v69, v141
	v_mov_b32_e32 v68, v141
	v_mov_b32_e32 v67, v141
	v_mov_b32_e32 v66, v141
	v_mov_b32_e32 v65, v141
	v_mov_b32_e32 v64, v141
	v_mov_b32_e32 v63, v141
	v_mov_b32_e32 v62, v141
	v_mov_b32_e32 v57, v141
	v_mov_b32_e32 v56, v141
	v_mov_b32_e32 v55, v141
	v_mov_b32_e32 v54, v141
	v_mov_b32_e32 v49, v141
	v_mov_b32_e32 v48, v141
	v_mov_b32_e32 v47, v141
	v_mov_b32_e32 v46, v141
	v_mov_b32_e32 v41, v141
	v_mov_b32_e32 v40, v141
	v_mov_b32_e32 v39, v141
	v_mov_b32_e32 v38, v141
	v_mov_b32_e32 v33, v141
	v_mov_b32_e32 v32, v141
	v_mov_b32_e32 v31, v141
	v_mov_b32_e32 v30, v141
	v_mov_b32_e32 v25, v141
	v_mov_b32_e32 v24, v141
	v_mov_b32_e32 v23, v141
	v_mov_b32_e32 v22, v141
	v_mov_b32_e32 v17, v141
	v_mov_b32_e32 v16, v141
	v_mov_b32_e32 v15, v141
	v_mov_b32_e32 v14, v141
	v_mov_b32_e32 v9, v141
	v_mov_b32_e32 v8, v141
	v_mov_b32_e32 v7, v141
	v_mov_b32_e32 v6, v141
	v_mov_b32_e32 v61, v141
	v_mov_b32_e32 v60, v141
	v_mov_b32_e32 v59, v141
	v_mov_b32_e32 v58, v141
	v_mov_b32_e32 v53, v141
	v_mov_b32_e32 v52, v141
	v_mov_b32_e32 v51, v141
	v_mov_b32_e32 v50, v141
	v_mov_b32_e32 v45, v141
	v_mov_b32_e32 v44, v141
	v_mov_b32_e32 v43, v141
	v_mov_b32_e32 v42, v141
	v_mov_b32_e32 v37, v141
	v_mov_b32_e32 v36, v141
	v_mov_b32_e32 v35, v141
	v_mov_b32_e32 v34, v141
	v_mov_b32_e32 v29, v141
	v_mov_b32_e32 v28, v141
	v_mov_b32_e32 v27, v141
	v_mov_b32_e32 v26, v141
	v_mov_b32_e32 v21, v141
	v_mov_b32_e32 v20, v141
	v_mov_b32_e32 v19, v141
	v_mov_b32_e32 v18, v141
	v_mov_b32_e32 v13, v141
	v_mov_b32_e32 v12, v141
	v_mov_b32_e32 v11, v141
	v_mov_b32_e32 v10, v141
	v_mov_b32_e32 v5, v141
	v_mov_b32_e32 v4, v141
	v_mov_b32_e32 v3, v141
	v_mov_b32_e32 v2, v141
	s_branch .LBB0_161

.LBB0_164:
	s_ashr_i32 s7, s6, 31
	s_lshl_b64 s[8:9], s[6:7], 19
	s_add_u32 s8, s64, s8
	s_addc_u32 s9, s65, s9
	s_ashr_i32 s5, s4, 31
	s_lshl_b64 s[10:11], s[4:5], 19
	s_add_u32 s10, s21, s10
	v_mov_b32_e32 v141, 0
	s_addc_u32 s11, s22, s11
	s_andn2_b64 vcc, exec, s[2:3]
	s_waitcnt vmcnt(0)
	s_cbranch_vccnz .Lzt_2
	v_mov_b64_e32 v[2:3], 0xb00
	v_cmp_lt_i64_e32 vcc, s[18:19], v[2:3]
	s_and_b64 s[18:19], vcc, exec
	s_cselect_b32 s5, s9, s15
	s_cselect_b32 s7, s8, s14
	s_cselect_b32 s43, s11, s17
	s_cselect_b32 s44, s10, s16
	s_add_u32 s14, s14, 0x40080
	s_addc_u32 s15, s15, 0
	s_add_u32 s45, s16, 0x100
	v_mov_b32_e32 v2, 0
	s_addc_u32 s46, s17, 0
	s_mov_b32 s16, 0
	v_mov_b32_e32 v3, v2
	v_mov_b32_e32 v4, v2
	v_mov_b32_e32 v5, v2
	v_mov_b32_e32 v10, v2
	v_mov_b32_e32 v11, v2
	v_mov_b32_e32 v12, v2
	v_mov_b32_e32 v13, v2
	v_mov_b32_e32 v18, v2
	v_mov_b32_e32 v19, v2
	v_mov_b32_e32 v20, v2
	v_mov_b32_e32 v21, v2
	v_mov_b32_e32 v26, v2
	v_mov_b32_e32 v27, v2
	v_mov_b32_e32 v28, v2
	v_mov_b32_e32 v29, v2
	v_mov_b32_e32 v34, v2
	v_mov_b32_e32 v35, v2
	v_mov_b32_e32 v36, v2
	v_mov_b32_e32 v37, v2
	v_mov_b32_e32 v42, v2
	v_mov_b32_e32 v43, v2
	v_mov_b32_e32 v44, v2
	v_mov_b32_e32 v45, v2
	v_mov_b32_e32 v50, v2
	v_mov_b32_e32 v51, v2
	v_mov_b32_e32 v52, v2
	v_mov_b32_e32 v53, v2
	v_mov_b32_e32 v58, v2
	v_mov_b32_e32 v59, v2
	v_mov_b32_e32 v60, v2
	v_mov_b32_e32 v61, v2
	v_mov_b32_e32 v6, v2
	v_mov_b32_e32 v7, v2
	v_mov_b32_e32 v8, v2
	v_mov_b32_e32 v9, v2
	v_mov_b32_e32 v14, v2
	v_mov_b32_e32 v15, v2
	v_mov_b32_e32 v16, v2
	v_mov_b32_e32 v17, v2
	v_mov_b32_e32 v22, v2
	v_mov_b32_e32 v23, v2
	v_mov_b32_e32 v24, v2
	v_mov_b32_e32 v25, v2
	v_mov_b32_e32 v30, v2
	v_mov_b32_e32 v31, v2
	v_mov_b32_e32 v32, v2
	v_mov_b32_e32 v33, v2
	v_mov_b32_e32 v38, v2
	v_mov_b32_e32 v39, v2
	v_mov_b32_e32 v40, v2
	v_mov_b32_e32 v41, v2
	v_mov_b32_e32 v46, v2
	v_mov_b32_e32 v47, v2
	v_mov_b32_e32 v48, v2
	v_mov_b32_e32 v49, v2
	v_mov_b32_e32 v54, v2
	v_mov_b32_e32 v55, v2
	v_mov_b32_e32 v56, v2
	v_mov_b32_e32 v57, v2
	v_mov_b32_e32 v62, v2
	v_mov_b32_e32 v63, v2
	v_mov_b32_e32 v64, v2
	v_mov_b32_e32 v65, v2
	v_mov_b32_e32 v66, v2
	v_mov_b32_e32 v67, v2
	v_mov_b32_e32 v68, v2
	v_mov_b32_e32 v69, v2
	v_mov_b32_e32 v74, v2
	v_mov_b32_e32 v75, v2
	v_mov_b32_e32 v76, v2
	v_mov_b32_e32 v77, v2
	v_mov_b32_e32 v90, v2
	v_mov_b32_e32 v91, v2
	v_mov_b32_e32 v92, v2
	v_mov_b32_e32 v93, v2
	v_mov_b32_e32 v106, v2
	v_mov_b32_e32 v107, v2
	v_mov_b32_e32 v108, v2
	v_mov_b32_e32 v109, v2
	v_mov_b32_e32 v114, v2
	v_mov_b32_e32 v115, v2
	v_mov_b32_e32 v116, v2
	v_mov_b32_e32 v117, v2
	v_mov_b32_e32 v122, v2
	v_mov_b32_e32 v123, v2
	v_mov_b32_e32 v124, v2
	v_mov_b32_e32 v125, v2
	v_mov_b32_e32 v130, v2
	v_mov_b32_e32 v131, v2
	v_mov_b32_e32 v132, v2
	v_mov_b32_e32 v133, v2
	v_mov_b32_e32 v142, v2
	v_mov_b32_e32 v143, v2
	v_mov_b32_e32 v144, v2
	v_mov_b32_e32 v145, v2
	v_mov_b32_e32 v70, v2
	v_mov_b32_e32 v71, v2
	v_mov_b32_e32 v72, v2
	v_mov_b32_e32 v73, v2
	v_mov_b32_e32 v78, v2
	v_mov_b32_e32 v79, v2
	v_mov_b32_e32 v80, v2
	v_mov_b32_e32 v81, v2
	v_mov_b32_e32 v94, v2
	v_mov_b32_e32 v95, v2
	v_mov_b32_e32 v96, v2
	v_mov_b32_e32 v97, v2
	v_mov_b32_e32 v110, v2
	v_mov_b32_e32 v111, v2
	v_mov_b32_e32 v112, v2
	v_mov_b32_e32 v113, v2
	v_mov_b32_e32 v118, v2
	v_mov_b32_e32 v119, v2
	v_mov_b32_e32 v120, v2
	v_mov_b32_e32 v121, v2
	v_mov_b32_e32 v126, v2
	v_mov_b32_e32 v127, v2
	v_mov_b32_e32 v128, v2
	v_mov_b32_e32 v129, v2
	v_mov_b32_e32 v134, v2
	v_mov_b32_e32 v135, v2
	v_mov_b32_e32 v136, v2
	v_mov_b32_e32 v137, v2
	v_mov_b32_e32 v138, v2
	v_mov_b32_e32 v139, v2
	v_mov_b32_e32 v140, v2
	v_mov_b32_e32 v141, v2

.Lzt_4:
	v_mov_b32_e32 v144, v145
	v_mov_b32_e32 v143, v145
	v_mov_b32_e32 v142, v145
	v_mov_b32_e32 v141, v145
	v_mov_b32_e32 v140, v145
	v_mov_b32_e32 v139, v145
	v_mov_b32_e32 v138, v145
	v_mov_b32_e32 v129, v145
	v_mov_b32_e32 v128, v145
	v_mov_b32_e32 v127, v145
	v_mov_b32_e32 v126, v145
	v_mov_b32_e32 v121, v145
	v_mov_b32_e32 v120, v145
	v_mov_b32_e32 v119, v145
	v_mov_b32_e32 v118, v145
	v_mov_b32_e32 v101, v145
	v_mov_b32_e32 v100, v145
	v_mov_b32_e32 v99, v145
	v_mov_b32_e32 v98, v145
	v_mov_b32_e32 v97, v145
	v_mov_b32_e32 v96, v145
	v_mov_b32_e32 v95, v145
	v_mov_b32_e32 v94, v145
	v_mov_b32_e32 v81, v145
	v_mov_b32_e32 v80, v145
	v_mov_b32_e32 v79, v145
	v_mov_b32_e32 v78, v145
	v_mov_b32_e32 v77, v145
	v_mov_b32_e32 v76, v145
	v_mov_b32_e32 v75, v145
	v_mov_b32_e32 v74, v145
	v_mov_b32_e32 v137, v145
	v_mov_b32_e32 v136, v145
	v_mov_b32_e32 v135, v145
	v_mov_b32_e32 v134, v145
	v_mov_b32_e32 v133, v145
	v_mov_b32_e32 v132, v145
	v_mov_b32_e32 v131, v145
	v_mov_b32_e32 v130, v145
	v_mov_b32_e32 v117, v145
	v_mov_b32_e32 v116, v145
	v_mov_b32_e32 v115, v145
	v_mov_b32_e32 v114, v145
	v_mov_b32_e32 v109, v145
	v_mov_b32_e32 v108, v145
	v_mov_b32_e32 v107, v145
	v_mov_b32_e32 v106, v145
	v_mov_b32_e32 v89, v145
	v_mov_b32_e32 v88, v145
	v_mov_b32_e32 v87, v145
	v_mov_b32_e32 v86, v145
	v_mov_b32_e32 v85, v145
	v_mov_b32_e32 v84, v145
	v_mov_b32_e32 v83, v145
	v_mov_b32_e32 v82, v145
	v_mov_b32_e32 v73, v145
	v_mov_b32_e32 v72, v145
	v_mov_b32_e32 v71, v145
	v_mov_b32_e32 v70, v145
	v_mov_b32_e32 v69, v145
	v_mov_b32_e32 v68, v145
	v_mov_b32_e32 v67, v145
	v_mov_b32_e32 v66, v145
	v_mov_b32_e32 v65, v145
	v_mov_b32_e32 v64, v145
	v_mov_b32_e32 v63, v145
	v_mov_b32_e32 v62, v145
	v_mov_b32_e32 v61, v145
	v_mov_b32_e32 v60, v145
	v_mov_b32_e32 v59, v145
	v_mov_b32_e32 v58, v145
	v_mov_b32_e32 v49, v145
	v_mov_b32_e32 v48, v145
	v_mov_b32_e32 v47, v145
	v_mov_b32_e32 v46, v145
	v_mov_b32_e32 v45, v145
	v_mov_b32_e32 v44, v145
	v_mov_b32_e32 v43, v145
	v_mov_b32_e32 v42, v145
	v_mov_b32_e32 v33, v145
	v_mov_b32_e32 v32, v145
	v_mov_b32_e32 v31, v145
	v_mov_b32_e32 v30, v145
	v_mov_b32_e32 v29, v145
	v_mov_b32_e32 v28, v145
	v_mov_b32_e32 v27, v145
	v_mov_b32_e32 v26, v145
	v_mov_b32_e32 v17, v145
	v_mov_b32_e32 v16, v145
	v_mov_b32_e32 v15, v145
	v_mov_b32_e32 v14, v145
	v_mov_b32_e32 v13, v145
	v_mov_b32_e32 v12, v145
	v_mov_b32_e32 v11, v145
	v_mov_b32_e32 v10, v145
	v_mov_b32_e32 v57, v145
	v_mov_b32_e32 v56, v145
	v_mov_b32_e32 v55, v145
	v_mov_b32_e32 v54, v145
	v_mov_b32_e32 v53, v145
	v_mov_b32_e32 v52, v145
	v_mov_b32_e32 v51, v145
	v_mov_b32_e32 v50, v145
	v_mov_b32_e32 v41, v145
	v_mov_b32_e32 v40, v145
	v_mov_b32_e32 v39, v145
	v_mov_b32_e32 v38, v145
	v_mov_b32_e32 v37, v145
	v_mov_b32_e32 v36, v145
	v_mov_b32_e32 v35, v145
	v_mov_b32_e32 v34, v145
	v_mov_b32_e32 v25, v145
	v_mov_b32_e32 v24, v145
	v_mov_b32_e32 v23, v145
	v_mov_b32_e32 v22, v145
	v_mov_b32_e32 v21, v145
	v_mov_b32_e32 v20, v145
	v_mov_b32_e32 v19, v145
	v_mov_b32_e32 v18, v145
	v_mov_b32_e32 v9, v145
	v_mov_b32_e32 v8, v145
	v_mov_b32_e32 v7, v145
	v_mov_b32_e32 v6, v145
	v_mov_b32_e32 v5, v145
	v_mov_b32_e32 v4, v145
	v_mov_b32_e32 v3, v145
	v_mov_b32_e32 v2, v145
	s_branch .LBB0_192

.LBB0_189:
	s_ashr_i32 s9, s8, 31
	s_lshl_b64 s[10:11], s[8:9], 19
	s_add_u32 s10, s23, s10
	s_addc_u32 s11, s24, s11
	s_ashr_i32 s7, s6, 31
	s_lshl_b64 s[12:13], s[6:7], 19
	s_add_u32 s12, s25, s12
	v_mov_b32_e32 v145, 0
	v_cmp_lt_i64_e64 s[0:1], s[0:1], v[162:163]
	s_addc_u32 s13, s26, s13
	s_andn2_b64 vcc, exec, s[4:5]
	s_waitcnt vmcnt(0)
	s_waitcnt lgkmcnt(0)
	s_cbranch_vccnz .Lzt_4
	s_and_b64 s[0:1], s[0:1], exec
	s_cselect_b32 s7, s11, s21
	s_cselect_b32 s9, s10, s20
	s_cselect_b32 s47, s13, s19
	s_cselect_b32 s48, s12, s18
	s_add_u32 s49, s18, 0x100
	s_addc_u32 s50, s19, 0
	s_add_u32 s0, s20, 0x40080
	v_mov_b32_e32 v2, 0
	s_addc_u32 s1, s21, 0
	s_mov_b32 s18, 0
	v_mov_b32_e32 v3, v2
	v_mov_b32_e32 v4, v2
	v_mov_b32_e32 v5, v2
	v_mov_b32_e32 v6, v2
	v_mov_b32_e32 v7, v2
	v_mov_b32_e32 v8, v2
	v_mov_b32_e32 v9, v2
	v_mov_b32_e32 v18, v2
	v_mov_b32_e32 v19, v2
	v_mov_b32_e32 v20, v2
	v_mov_b32_e32 v21, v2
	v_mov_b32_e32 v22, v2
	v_mov_b32_e32 v23, v2
	v_mov_b32_e32 v24, v2
	v_mov_b32_e32 v25, v2
	v_mov_b32_e32 v34, v2
	v_mov_b32_e32 v35, v2
	v_mov_b32_e32 v36, v2
	v_mov_b32_e32 v37, v2
	v_mov_b32_e32 v38, v2
	v_mov_b32_e32 v39, v2
	v_mov_b32_e32 v40, v2
	v_mov_b32_e32 v41, v2
	v_mov_b32_e32 v50, v2
	v_mov_b32_e32 v51, v2
	v_mov_b32_e32 v52, v2
	v_mov_b32_e32 v53, v2
	v_mov_b32_e32 v54, v2
	v_mov_b32_e32 v55, v2
	v_mov_b32_e32 v56, v2
	v_mov_b32_e32 v57, v2
	v_mov_b32_e32 v10, v2
	v_mov_b32_e32 v11, v2
	v_mov_b32_e32 v12, v2
	v_mov_b32_e32 v13, v2
	v_mov_b32_e32 v14, v2
	v_mov_b32_e32 v15, v2
	v_mov_b32_e32 v16, v2
	v_mov_b32_e32 v17, v2
	v_mov_b32_e32 v26, v2
	v_mov_b32_e32 v27, v2
	v_mov_b32_e32 v28, v2
	v_mov_b32_e32 v29, v2
	v_mov_b32_e32 v30, v2
	v_mov_b32_e32 v31, v2
	v_mov_b32_e32 v32, v2
	v_mov_b32_e32 v33, v2
	v_mov_b32_e32 v42, v2
	v_mov_b32_e32 v43, v2
	v_mov_b32_e32 v44, v2
	v_mov_b32_e32 v45, v2
	v_mov_b32_e32 v46, v2
	v_mov_b32_e32 v47, v2
	v_mov_b32_e32 v48, v2
	v_mov_b32_e32 v49, v2
	v_mov_b32_e32 v58, v2
	v_mov_b32_e32 v59, v2
	v_mov_b32_e32 v60, v2
	v_mov_b32_e32 v61, v2
	v_mov_b32_e32 v62, v2
	v_mov_b32_e32 v63, v2
	v_mov_b32_e32 v64, v2
	v_mov_b32_e32 v65, v2
	v_mov_b32_e32 v66, v2
	v_mov_b32_e32 v67, v2
	v_mov_b32_e32 v68, v2
	v_mov_b32_e32 v69, v2
	v_mov_b32_e32 v70, v2
	v_mov_b32_e32 v71, v2
	v_mov_b32_e32 v72, v2
	v_mov_b32_e32 v73, v2
	v_mov_b32_e32 v82, v2
	v_mov_b32_e32 v83, v2
	v_mov_b32_e32 v84, v2
	v_mov_b32_e32 v85, v2
	v_mov_b32_e32 v86, v2
	v_mov_b32_e32 v87, v2
	v_mov_b32_e32 v88, v2
	v_mov_b32_e32 v89, v2
	v_mov_b32_e32 v106, v2
	v_mov_b32_e32 v107, v2
	v_mov_b32_e32 v108, v2
	v_mov_b32_e32 v109, v2
	v_mov_b32_e32 v114, v2
	v_mov_b32_e32 v115, v2
	v_mov_b32_e32 v116, v2
	v_mov_b32_e32 v117, v2
	v_mov_b32_e32 v130, v2
	v_mov_b32_e32 v131, v2
	v_mov_b32_e32 v132, v2
	v_mov_b32_e32 v133, v2
	v_mov_b32_e32 v134, v2
	v_mov_b32_e32 v135, v2
	v_mov_b32_e32 v136, v2
	v_mov_b32_e32 v137, v2
	v_mov_b32_e32 v74, v2
	v_mov_b32_e32 v75, v2
	v_mov_b32_e32 v76, v2
	v_mov_b32_e32 v77, v2
	v_mov_b32_e32 v78, v2
	v_mov_b32_e32 v79, v2
	v_mov_b32_e32 v80, v2
	v_mov_b32_e32 v81, v2
	v_mov_b32_e32 v94, v2
	v_mov_b32_e32 v95, v2
	v_mov_b32_e32 v96, v2
	v_mov_b32_e32 v97, v2
	v_mov_b32_e32 v98, v2
	v_mov_b32_e32 v99, v2
	v_mov_b32_e32 v100, v2
	v_mov_b32_e32 v101, v2
	v_mov_b32_e32 v118, v2
	v_mov_b32_e32 v119, v2
	v_mov_b32_e32 v120, v2
	v_mov_b32_e32 v121, v2
	v_mov_b32_e32 v126, v2
	v_mov_b32_e32 v127, v2
	v_mov_b32_e32 v128, v2
	v_mov_b32_e32 v129, v2
	v_mov_b32_e32 v138, v2
	v_mov_b32_e32 v139, v2
	v_mov_b32_e32 v140, v2
	v_mov_b32_e32 v141, v2
	v_mov_b32_e32 v142, v2
	v_mov_b32_e32 v143, v2
	v_mov_b32_e32 v144, v2
	v_mov_b32_e32 v145, v2

.Lzt_10:
	v_mov_b32_e32 v120, v121
	v_mov_b32_e32 v119, v121
	v_mov_b32_e32 v118, v121
	v_mov_b32_e32 v125, v121
	v_mov_b32_e32 v124, v121
	v_mov_b32_e32 v123, v121
	v_mov_b32_e32 v122, v121
	v_mov_b32_e32 v105, v121
	v_mov_b32_e32 v104, v121
	v_mov_b32_e32 v103, v121
	v_mov_b32_e32 v102, v121
	v_mov_b32_e32 v109, v121
	v_mov_b32_e32 v108, v121
	v_mov_b32_e32 v107, v121
	v_mov_b32_e32 v106, v121
	v_mov_b32_e32 v89, v121
	v_mov_b32_e32 v88, v121
	v_mov_b32_e32 v87, v121
	v_mov_b32_e32 v86, v121
	v_mov_b32_e32 v93, v121
	v_mov_b32_e32 v92, v121
	v_mov_b32_e32 v91, v121
	v_mov_b32_e32 v90, v121
	v_mov_b32_e32 v73, v121
	v_mov_b32_e32 v72, v121
	v_mov_b32_e32 v71, v121
	v_mov_b32_e32 v70, v121
	v_mov_b32_e32 v77, v121
	v_mov_b32_e32 v76, v121
	v_mov_b32_e32 v75, v121
	v_mov_b32_e32 v74, v121
	v_mov_b32_e32 v117, v121
	v_mov_b32_e32 v116, v121
	v_mov_b32_e32 v115, v121
	v_mov_b32_e32 v114, v121
	v_mov_b32_e32 v129, v121
	v_mov_b32_e32 v128, v121
	v_mov_b32_e32 v127, v121
	v_mov_b32_e32 v126, v121
	v_mov_b32_e32 v101, v121
	v_mov_b32_e32 v100, v121
	v_mov_b32_e32 v99, v121
	v_mov_b32_e32 v98, v121
	v_mov_b32_e32 v113, v121
	v_mov_b32_e32 v112, v121
	v_mov_b32_e32 v111, v121
	v_mov_b32_e32 v110, v121
	v_mov_b32_e32 v85, v121
	v_mov_b32_e32 v84, v121
	v_mov_b32_e32 v83, v121
	v_mov_b32_e32 v82, v121
	v_mov_b32_e32 v97, v121
	v_mov_b32_e32 v96, v121
	v_mov_b32_e32 v95, v121
	v_mov_b32_e32 v94, v121
	v_mov_b32_e32 v69, v121
	v_mov_b32_e32 v68, v121
	v_mov_b32_e32 v67, v121
	v_mov_b32_e32 v66, v121
	v_mov_b32_e32 v81, v121
	v_mov_b32_e32 v80, v121
	v_mov_b32_e32 v79, v121
	v_mov_b32_e32 v78, v121
	v_mov_b32_e32 v57, v121
	v_mov_b32_e32 v56, v121
	v_mov_b32_e32 v55, v121
	v_mov_b32_e32 v54, v121
	v_mov_b32_e32 v61, v121
	v_mov_b32_e32 v60, v121
	v_mov_b32_e32 v59, v121
	v_mov_b32_e32 v58, v121
	v_mov_b32_e32 v41, v121
	v_mov_b32_e32 v40, v121
	v_mov_b32_e32 v39, v121
	v_mov_b32_e32 v38, v121
	v_mov_b32_e32 v45, v121
	v_mov_b32_e32 v44, v121
	v_mov_b32_e32 v43, v121
	v_mov_b32_e32 v42, v121
	v_mov_b32_e32 v25, v121
	v_mov_b32_e32 v24, v121
	v_mov_b32_e32 v23, v121
	v_mov_b32_e32 v22, v121
	v_mov_b32_e32 v29, v121
	v_mov_b32_e32 v28, v121
	v_mov_b32_e32 v27, v121
	v_mov_b32_e32 v26, v121
	v_mov_b32_e32 v13, v121
	v_mov_b32_e32 v12, v121
	v_mov_b32_e32 v11, v121
	v_mov_b32_e32 v10, v121
	v_mov_b32_e32 v17, v121
	v_mov_b32_e32 v16, v121
	v_mov_b32_e32 v15, v121
	v_mov_b32_e32 v14, v121
	v_mov_b32_e32 v53, v121
	v_mov_b32_e32 v52, v121
	v_mov_b32_e32 v51, v121
	v_mov_b32_e32 v50, v121
	v_mov_b32_e32 v65, v121
	v_mov_b32_e32 v64, v121
	v_mov_b32_e32 v63, v121
	v_mov_b32_e32 v62, v121
	v_mov_b32_e32 v37, v121
	v_mov_b32_e32 v36, v121
	v_mov_b32_e32 v35, v121
	v_mov_b32_e32 v34, v121
	v_mov_b32_e32 v49, v121
	v_mov_b32_e32 v48, v121
	v_mov_b32_e32 v47, v121
	v_mov_b32_e32 v46, v121
	v_mov_b32_e32 v21, v121
	v_mov_b32_e32 v20, v121
	v_mov_b32_e32 v19, v121
	v_mov_b32_e32 v18, v121
	v_mov_b32_e32 v33, v121
	v_mov_b32_e32 v32, v121
	v_mov_b32_e32 v31, v121
	v_mov_b32_e32 v30, v121
	v_mov_b32_e32 v5, v121
	v_mov_b32_e32 v4, v121
	v_mov_b32_e32 v3, v121
	v_mov_b32_e32 v2, v121
	v_mov_b32_e32 v9, v121
	v_mov_b32_e32 v8, v121
	v_mov_b32_e32 v7, v121
	v_mov_b32_e32 v6, v121
	s_branch .LBB0_455

.LBB0_452:
	s_ashr_i32 s11, s10, 31
	s_lshl_b64 s[12:13], s[10:11], 19
	s_add_u32 s12, s64, s12
	s_addc_u32 s13, s65, s13
	s_ashr_i32 s9, s8, 31
	s_lshl_b64 s[14:15], s[8:9], 19
	s_add_u32 s14, s25, s14
	s_waitcnt vmcnt(0)
	v_mov_b32_e32 v121, 0
	s_addc_u32 s15, s26, s15
	s_andn2_b64 vcc, exec, s[6:7]
	s_cbranch_vccnz .Lzt_10
	v_mov_b64_e32 v[2:3], 0x280
	v_cmp_lt_i64_e32 vcc, s[22:23], v[2:3]
	s_and_b64 s[22:23], vcc, exec
	s_cselect_b32 s9, s13, s19
	s_cselect_b32 s11, s12, s18
	s_cselect_b32 s48, s15, s21
	s_cselect_b32 s49, s14, s20
	s_add_u32 s18, s18, 0x40080
	s_addc_u32 s19, s19, 0
	s_add_u32 s50, s20, 0x100
	v_mov_b32_e32 v6, 0
	s_addc_u32 s51, s21, 0
	s_mov_b32 s20, 0
	v_mov_b32_e32 v7, v6
	v_mov_b32_e32 v8, v6
	v_mov_b32_e32 v9, v6
	v_mov_b32_e32 v2, v6
	v_mov_b32_e32 v3, v6
	v_mov_b32_e32 v4, v6
	v_mov_b32_e32 v5, v6
	v_mov_b32_e32 v30, v6
	v_mov_b32_e32 v31, v6
	v_mov_b32_e32 v32, v6
	v_mov_b32_e32 v33, v6
	v_mov_b32_e32 v18, v6
	v_mov_b32_e32 v19, v6
	v_mov_b32_e32 v20, v6
	v_mov_b32_e32 v21, v6
	v_mov_b32_e32 v46, v6
	v_mov_b32_e32 v47, v6
	v_mov_b32_e32 v48, v6
	v_mov_b32_e32 v49, v6
	v_mov_b32_e32 v34, v6
	v_mov_b32_e32 v35, v6
	v_mov_b32_e32 v36, v6
	v_mov_b32_e32 v37, v6
	v_mov_b32_e32 v62, v6
	v_mov_b32_e32 v63, v6
	v_mov_b32_e32 v64, v6
	v_mov_b32_e32 v65, v6
	v_mov_b32_e32 v50, v6
	v_mov_b32_e32 v51, v6
	v_mov_b32_e32 v52, v6
	v_mov_b32_e32 v53, v6
	v_mov_b32_e32 v14, v6
	v_mov_b32_e32 v15, v6
	v_mov_b32_e32 v16, v6
	v_mov_b32_e32 v17, v6
	v_mov_b32_e32 v10, v6
	v_mov_b32_e32 v11, v6
	v_mov_b32_e32 v12, v6
	v_mov_b32_e32 v13, v6
	v_mov_b32_e32 v26, v6
	v_mov_b32_e32 v27, v6
	v_mov_b32_e32 v28, v6
	v_mov_b32_e32 v29, v6
	v_mov_b32_e32 v22, v6
	v_mov_b32_e32 v23, v6
	v_mov_b32_e32 v24, v6
	v_mov_b32_e32 v25, v6
	v_mov_b32_e32 v42, v6
	v_mov_b32_e32 v43, v6
	v_mov_b32_e32 v44, v6
	v_mov_b32_e32 v45, v6
	v_mov_b32_e32 v38, v6
	v_mov_b32_e32 v39, v6
	v_mov_b32_e32 v40, v6
	v_mov_b32_e32 v41, v6
	v_mov_b32_e32 v58, v6
	v_mov_b32_e32 v59, v6
	v_mov_b32_e32 v60, v6
	v_mov_b32_e32 v61, v6
	v_mov_b32_e32 v54, v6
	v_mov_b32_e32 v55, v6
	v_mov_b32_e32 v56, v6
	v_mov_b32_e32 v57, v6
	v_mov_b32_e32 v78, v6
	v_mov_b32_e32 v79, v6
	v_mov_b32_e32 v80, v6
	v_mov_b32_e32 v81, v6
	v_mov_b32_e32 v66, v6
	v_mov_b32_e32 v67, v6
	v_mov_b32_e32 v68, v6
	v_mov_b32_e32 v69, v6
	v_mov_b32_e32 v94, v6
	v_mov_b32_e32 v95, v6
	v_mov_b32_e32 v96, v6
	v_mov_b32_e32 v97, v6
	v_mov_b32_e32 v82, v6
	v_mov_b32_e32 v83, v6
	v_mov_b32_e32 v84, v6
	v_mov_b32_e32 v85, v6
	v_mov_b32_e32 v110, v6
	v_mov_b32_e32 v111, v6
	v_mov_b32_e32 v112, v6
	v_mov_b32_e32 v113, v6
	v_mov_b32_e32 v98, v6
	v_mov_b32_e32 v99, v6
	v_mov_b32_e32 v100, v6
	v_mov_b32_e32 v101, v6
	v_mov_b32_e32 v126, v6
	v_mov_b32_e32 v127, v6
	v_mov_b32_e32 v128, v6
	v_mov_b32_e32 v129, v6
	v_mov_b32_e32 v114, v6
	v_mov_b32_e32 v115, v6
	v_mov_b32_e32 v116, v6
	v_mov_b32_e32 v117, v6
	v_mov_b32_e32 v74, v6
	v_mov_b32_e32 v75, v6
	v_mov_b32_e32 v76, v6
	v_mov_b32_e32 v77, v6
	v_mov_b32_e32 v70, v6
	v_mov_b32_e32 v71, v6
	v_mov_b32_e32 v72, v6
	v_mov_b32_e32 v73, v6
	v_mov_b32_e32 v90, v6
	v_mov_b32_e32 v91, v6
	v_mov_b32_e32 v92, v6
	v_mov_b32_e32 v93, v6
	v_mov_b32_e32 v86, v6
	v_mov_b32_e32 v87, v6
	v_mov_b32_e32 v88, v6
	v_mov_b32_e32 v89, v6
	v_mov_b32_e32 v106, v6
	v_mov_b32_e32 v107, v6
	v_mov_b32_e32 v108, v6
	v_mov_b32_e32 v109, v6
	v_mov_b32_e32 v102, v6
	v_mov_b32_e32 v103, v6
	v_mov_b32_e32 v104, v6
	v_mov_b32_e32 v105, v6
	v_mov_b32_e32 v122, v6
	v_mov_b32_e32 v123, v6
	v_mov_b32_e32 v124, v6
	v_mov_b32_e32 v125, v6
	v_mov_b32_e32 v118, v6
	v_mov_b32_e32 v119, v6
	v_mov_b32_e32 v120, v6
	v_mov_b32_e32 v121, v6

.Lzt_12:
	v_mov_b32_e32 v144, v145
	v_mov_b32_e32 v143, v145
	v_mov_b32_e32 v142, v145
	v_mov_b32_e32 v141, v145
	v_mov_b32_e32 v140, v145
	v_mov_b32_e32 v139, v145
	v_mov_b32_e32 v138, v145
	v_mov_b32_e32 v129, v145
	v_mov_b32_e32 v128, v145
	v_mov_b32_e32 v127, v145
	v_mov_b32_e32 v126, v145
	v_mov_b32_e32 v121, v145
	v_mov_b32_e32 v120, v145
	v_mov_b32_e32 v119, v145
	v_mov_b32_e32 v118, v145
	v_mov_b32_e32 v97, v145
	v_mov_b32_e32 v96, v145
	v_mov_b32_e32 v95, v145
	v_mov_b32_e32 v94, v145
	v_mov_b32_e32 v93, v145
	v_mov_b32_e32 v92, v145
	v_mov_b32_e32 v91, v145
	v_mov_b32_e32 v90, v145
	v_mov_b32_e32 v81, v145
	v_mov_b32_e32 v80, v145
	v_mov_b32_e32 v79, v145
	v_mov_b32_e32 v78, v145
	v_mov_b32_e32 v77, v145
	v_mov_b32_e32 v76, v145
	v_mov_b32_e32 v75, v145
	v_mov_b32_e32 v74, v145
	v_mov_b32_e32 v137, v145
	v_mov_b32_e32 v136, v145
	v_mov_b32_e32 v135, v145
	v_mov_b32_e32 v134, v145
	v_mov_b32_e32 v133, v145
	v_mov_b32_e32 v132, v145
	v_mov_b32_e32 v131, v145
	v_mov_b32_e32 v130, v145
	v_mov_b32_e32 v113, v145
	v_mov_b32_e32 v112, v145
	v_mov_b32_e32 v111, v145
	v_mov_b32_e32 v110, v145
	v_mov_b32_e32 v105, v145
	v_mov_b32_e32 v104, v145
	v_mov_b32_e32 v103, v145
	v_mov_b32_e32 v102, v145
	v_mov_b32_e32 v89, v145
	v_mov_b32_e32 v88, v145
	v_mov_b32_e32 v87, v145
	v_mov_b32_e32 v86, v145
	v_mov_b32_e32 v85, v145
	v_mov_b32_e32 v84, v145
	v_mov_b32_e32 v83, v145
	v_mov_b32_e32 v82, v145
	v_mov_b32_e32 v73, v145
	v_mov_b32_e32 v72, v145
	v_mov_b32_e32 v71, v145
	v_mov_b32_e32 v70, v145
	v_mov_b32_e32 v69, v145
	v_mov_b32_e32 v68, v145
	v_mov_b32_e32 v67, v145
	v_mov_b32_e32 v66, v145
	v_mov_b32_e32 v65, v145
	v_mov_b32_e32 v64, v145
	v_mov_b32_e32 v63, v145
	v_mov_b32_e32 v62, v145
	v_mov_b32_e32 v61, v145
	v_mov_b32_e32 v60, v145
	v_mov_b32_e32 v59, v145
	v_mov_b32_e32 v58, v145
	v_mov_b32_e32 v49, v145
	v_mov_b32_e32 v48, v145
	v_mov_b32_e32 v47, v145
	v_mov_b32_e32 v46, v145
	v_mov_b32_e32 v45, v145
	v_mov_b32_e32 v44, v145
	v_mov_b32_e32 v43, v145
	v_mov_b32_e32 v42, v145
	v_mov_b32_e32 v33, v145
	v_mov_b32_e32 v32, v145
	v_mov_b32_e32 v31, v145
	v_mov_b32_e32 v30, v145
	v_mov_b32_e32 v29, v145
	v_mov_b32_e32 v28, v145
	v_mov_b32_e32 v27, v145
	v_mov_b32_e32 v26, v145
	v_mov_b32_e32 v17, v145
	v_mov_b32_e32 v16, v145
	v_mov_b32_e32 v15, v145
	v_mov_b32_e32 v14, v145
	v_mov_b32_e32 v13, v145
	v_mov_b32_e32 v12, v145
	v_mov_b32_e32 v11, v145
	v_mov_b32_e32 v10, v145
	v_mov_b32_e32 v57, v145
	v_mov_b32_e32 v56, v145
	v_mov_b32_e32 v55, v145
	v_mov_b32_e32 v54, v145
	v_mov_b32_e32 v53, v145
	v_mov_b32_e32 v52, v145
	v_mov_b32_e32 v51, v145
	v_mov_b32_e32 v50, v145
	v_mov_b32_e32 v41, v145
	v_mov_b32_e32 v40, v145
	v_mov_b32_e32 v39, v145
	v_mov_b32_e32 v38, v145
	v_mov_b32_e32 v37, v145
	v_mov_b32_e32 v36, v145
	v_mov_b32_e32 v35, v145
	v_mov_b32_e32 v34, v145
	v_mov_b32_e32 v25, v145
	v_mov_b32_e32 v24, v145
	v_mov_b32_e32 v23, v145
	v_mov_b32_e32 v22, v145
	v_mov_b32_e32 v21, v145
	v_mov_b32_e32 v20, v145
	v_mov_b32_e32 v19, v145
	v_mov_b32_e32 v18, v145
	v_mov_b32_e32 v9, v145
	v_mov_b32_e32 v8, v145
	v_mov_b32_e32 v7, v145
	v_mov_b32_e32 v6, v145
	v_mov_b32_e32 v5, v145
	v_mov_b32_e32 v4, v145
	v_mov_b32_e32 v3, v145
	v_mov_b32_e32 v2, v145
	s_branch .LBB0_501

.LBB0_498:
	v_mov_b32_e32 v145, 0
	s_andn2_b64 vcc, exec, s[6:7]
	s_waitcnt lgkmcnt(0)
	s_cbranch_vccnz .Lzt_12
	s_add_u32 s45, s8, 0x100
	s_addc_u32 s46, s9, 0
	s_add_u32 s8, s10, 0xc000
	v_mov_b32_e32 v2, 0
	s_addc_u32 s9, s11, 0
	s_mov_b32 s10, 0
	v_mov_b32_e32 v3, v2
	v_mov_b32_e32 v4, v2
	v_mov_b32_e32 v5, v2
	v_mov_b32_e32 v6, v2
	v_mov_b32_e32 v7, v2
	v_mov_b32_e32 v8, v2
	v_mov_b32_e32 v9, v2
	v_mov_b32_e32 v18, v2
	v_mov_b32_e32 v19, v2
	v_mov_b32_e32 v20, v2
	v_mov_b32_e32 v21, v2
	v_mov_b32_e32 v22, v2
	v_mov_b32_e32 v23, v2
	v_mov_b32_e32 v24, v2
	v_mov_b32_e32 v25, v2
	v_mov_b32_e32 v34, v2
	v_mov_b32_e32 v35, v2
	v_mov_b32_e32 v36, v2
	v_mov_b32_e32 v37, v2
	v_mov_b32_e32 v38, v2
	v_mov_b32_e32 v39, v2
	v_mov_b32_e32 v40, v2
	v_mov_b32_e32 v41, v2
	v_mov_b32_e32 v50, v2
	v_mov_b32_e32 v51, v2
	v_mov_b32_e32 v52, v2
	v_mov_b32_e32 v53, v2
	v_mov_b32_e32 v54, v2
	v_mov_b32_e32 v55, v2
	v_mov_b32_e32 v56, v2
	v_mov_b32_e32 v57, v2
	v_mov_b32_e32 v10, v2
	v_mov_b32_e32 v11, v2
	v_mov_b32_e32 v12, v2
	v_mov_b32_e32 v13, v2
	v_mov_b32_e32 v14, v2
	v_mov_b32_e32 v15, v2
	v_mov_b32_e32 v16, v2
	v_mov_b32_e32 v17, v2
	v_mov_b32_e32 v26, v2
	v_mov_b32_e32 v27, v2
	v_mov_b32_e32 v28, v2
	v_mov_b32_e32 v29, v2
	v_mov_b32_e32 v30, v2
	v_mov_b32_e32 v31, v2
	v_mov_b32_e32 v32, v2
	v_mov_b32_e32 v33, v2
	v_mov_b32_e32 v42, v2
	v_mov_b32_e32 v43, v2
	v_mov_b32_e32 v44, v2
	v_mov_b32_e32 v45, v2
	v_mov_b32_e32 v46, v2
	v_mov_b32_e32 v47, v2
	v_mov_b32_e32 v48, v2
	v_mov_b32_e32 v49, v2
	v_mov_b32_e32 v58, v2
	v_mov_b32_e32 v59, v2
	v_mov_b32_e32 v60, v2
	v_mov_b32_e32 v61, v2
	v_mov_b32_e32 v62, v2
	v_mov_b32_e32 v63, v2
	v_mov_b32_e32 v64, v2
	v_mov_b32_e32 v65, v2
	v_mov_b32_e32 v66, v2
	v_mov_b32_e32 v67, v2
	v_mov_b32_e32 v68, v2
	v_mov_b32_e32 v69, v2
	v_mov_b32_e32 v70, v2
	v_mov_b32_e32 v71, v2
	v_mov_b32_e32 v72, v2
	v_mov_b32_e32 v73, v2
	v_mov_b32_e32 v82, v2
	v_mov_b32_e32 v83, v2
	v_mov_b32_e32 v84, v2
	v_mov_b32_e32 v85, v2
	v_mov_b32_e32 v86, v2
	v_mov_b32_e32 v87, v2
	v_mov_b32_e32 v88, v2
	v_mov_b32_e32 v89, v2
	v_mov_b32_e32 v102, v2
	v_mov_b32_e32 v103, v2
	v_mov_b32_e32 v104, v2
	v_mov_b32_e32 v105, v2
	v_mov_b32_e32 v110, v2
	v_mov_b32_e32 v111, v2
	v_mov_b32_e32 v112, v2
	v_mov_b32_e32 v113, v2
	v_mov_b32_e32 v130, v2
	v_mov_b32_e32 v131, v2
	v_mov_b32_e32 v132, v2
	v_mov_b32_e32 v133, v2
	v_mov_b32_e32 v134, v2
	v_mov_b32_e32 v135, v2
	v_mov_b32_e32 v136, v2
	v_mov_b32_e32 v137, v2
	v_mov_b32_e32 v74, v2
	v_mov_b32_e32 v75, v2
	v_mov_b32_e32 v76, v2
	v_mov_b32_e32 v77, v2
	v_mov_b32_e32 v78, v2
	v_mov_b32_e32 v79, v2
	v_mov_b32_e32 v80, v2
	v_mov_b32_e32 v81, v2
	v_mov_b32_e32 v90, v2
	v_mov_b32_e32 v91, v2
	v_mov_b32_e32 v92, v2
	v_mov_b32_e32 v93, v2
	v_mov_b32_e32 v94, v2
	v_mov_b32_e32 v95, v2
	v_mov_b32_e32 v96, v2
	v_mov_b32_e32 v97, v2
	v_mov_b32_e32 v118, v2
	v_mov_b32_e32 v119, v2
	v_mov_b32_e32 v120, v2
	v_mov_b32_e32 v121, v2
	v_mov_b32_e32 v126, v2
	v_mov_b32_e32 v127, v2
	v_mov_b32_e32 v128, v2
	v_mov_b32_e32 v129, v2
	v_mov_b32_e32 v138, v2
	v_mov_b32_e32 v139, v2
	v_mov_b32_e32 v140, v2
	v_mov_b32_e32 v141, v2
	v_mov_b32_e32 v142, v2
	v_mov_b32_e32 v143, v2
	v_mov_b32_e32 v144, v2
	v_mov_b32_e32 v145, v2

.Lzt_14:
	v_mov_b32_e32 v144, v145
	v_mov_b32_e32 v143, v145
	v_mov_b32_e32 v142, v145
	v_mov_b32_e32 v137, v145
	v_mov_b32_e32 v136, v145
	v_mov_b32_e32 v135, v145
	v_mov_b32_e32 v134, v145
	v_mov_b32_e32 v129, v145
	v_mov_b32_e32 v128, v145
	v_mov_b32_e32 v127, v145
	v_mov_b32_e32 v126, v145
	v_mov_b32_e32 v121, v145
	v_mov_b32_e32 v120, v145
	v_mov_b32_e32 v119, v145
	v_mov_b32_e32 v118, v145
	v_mov_b32_e32 v113, v145
	v_mov_b32_e32 v112, v145
	v_mov_b32_e32 v111, v145
	v_mov_b32_e32 v110, v145
	v_mov_b32_e32 v105, v145
	v_mov_b32_e32 v104, v145
	v_mov_b32_e32 v103, v145
	v_mov_b32_e32 v102, v145
	v_mov_b32_e32 v97, v145
	v_mov_b32_e32 v96, v145
	v_mov_b32_e32 v95, v145
	v_mov_b32_e32 v94, v145
	v_mov_b32_e32 v89, v145
	v_mov_b32_e32 v88, v145
	v_mov_b32_e32 v87, v145
	v_mov_b32_e32 v86, v145
	v_mov_b32_e32 v141, v145
	v_mov_b32_e32 v140, v145
	v_mov_b32_e32 v139, v145
	v_mov_b32_e32 v138, v145
	v_mov_b32_e32 v133, v145
	v_mov_b32_e32 v132, v145
	v_mov_b32_e32 v131, v145
	v_mov_b32_e32 v130, v145
	v_mov_b32_e32 v125, v145
	v_mov_b32_e32 v124, v145
	v_mov_b32_e32 v123, v145
	v_mov_b32_e32 v122, v145
	v_mov_b32_e32 v117, v145
	v_mov_b32_e32 v116, v145
	v_mov_b32_e32 v115, v145
	v_mov_b32_e32 v114, v145
	v_mov_b32_e32 v109, v145
	v_mov_b32_e32 v108, v145
	v_mov_b32_e32 v107, v145
	v_mov_b32_e32 v106, v145
	v_mov_b32_e32 v101, v145
	v_mov_b32_e32 v100, v145
	v_mov_b32_e32 v99, v145
	v_mov_b32_e32 v98, v145
	v_mov_b32_e32 v93, v145
	v_mov_b32_e32 v92, v145
	v_mov_b32_e32 v91, v145
	v_mov_b32_e32 v90, v145
	v_mov_b32_e32 v85, v145
	v_mov_b32_e32 v84, v145
	v_mov_b32_e32 v83, v145
	v_mov_b32_e32 v82, v145
	v_mov_b32_e32 v81, v145
	v_mov_b32_e32 v80, v145
	v_mov_b32_e32 v79, v145
	v_mov_b32_e32 v78, v145
	v_mov_b32_e32 v73, v145
	v_mov_b32_e32 v72, v145
	v_mov_b32_e32 v71, v145
	v_mov_b32_e32 v70, v145
	v_mov_b32_e32 v57, v145
	v_mov_b32_e32 v56, v145
	v_mov_b32_e32 v55, v145
	v_mov_b32_e32 v54, v145
	v_mov_b32_e32 v49, v145
	v_mov_b32_e32 v48, v145
	v_mov_b32_e32 v47, v145
	v_mov_b32_e32 v46, v145
	v_mov_b32_e32 v33, v145
	v_mov_b32_e32 v32, v145
	v_mov_b32_e32 v31, v145
	v_mov_b32_e32 v30, v145
	v_mov_b32_e32 v25, v145
	v_mov_b32_e32 v24, v145
	v_mov_b32_e32 v23, v145
	v_mov_b32_e32 v22, v145
	v_mov_b32_e32 v17, v145
	v_mov_b32_e32 v16, v145
	v_mov_b32_e32 v15, v145
	v_mov_b32_e32 v14, v145
	v_mov_b32_e32 v9, v145
	v_mov_b32_e32 v8, v145
	v_mov_b32_e32 v7, v145
	v_mov_b32_e32 v6, v145
	v_mov_b32_e32 v77, v145
	v_mov_b32_e32 v76, v145
	v_mov_b32_e32 v75, v145
	v_mov_b32_e32 v74, v145
	v_mov_b32_e32 v69, v145
	v_mov_b32_e32 v68, v145
	v_mov_b32_e32 v67, v145
	v_mov_b32_e32 v66, v145
	v_mov_b32_e32 v53, v145
	v_mov_b32_e32 v52, v145
	v_mov_b32_e32 v51, v145
	v_mov_b32_e32 v50, v145
	v_mov_b32_e32 v45, v145
	v_mov_b32_e32 v44, v145
	v_mov_b32_e32 v43, v145
	v_mov_b32_e32 v42, v145
	v_mov_b32_e32 v29, v145
	v_mov_b32_e32 v28, v145
	v_mov_b32_e32 v27, v145
	v_mov_b32_e32 v26, v145
	v_mov_b32_e32 v21, v145
	v_mov_b32_e32 v20, v145
	v_mov_b32_e32 v19, v145
	v_mov_b32_e32 v18, v145
	v_mov_b32_e32 v13, v145
	v_mov_b32_e32 v12, v145
	v_mov_b32_e32 v11, v145
	v_mov_b32_e32 v10, v145
	v_mov_b32_e32 v5, v145
	v_mov_b32_e32 v4, v145
	v_mov_b32_e32 v3, v145
	v_mov_b32_e32 v2, v145
	s_branch .LBB0_535

.LBB0_532:
	s_ashr_i32 s13, s12, 31
	s_lshl_b64 s[14:15], s[12:13], 19
	s_add_u32 s14, s27, s14
	s_addc_u32 s15, s28, s15
	s_ashr_i32 s11, s10, 31
	s_lshl_b64 s[16:17], s[10:11], 19
	s_add_u32 s16, s29, s16
	v_mov_b32_e32 v145, 0
	s_addc_u32 s17, s30, s17
	s_andn2_b64 vcc, exec, s[6:7]
	s_waitcnt vmcnt(0)
	s_cbranch_vccnz .Lzt_14
	v_mov_b64_e32 v[2:3], 0x180
	v_cmp_lt_i64_e32 vcc, s[24:25], v[2:3]
	s_and_b64 s[24:25], vcc, exec
	s_cselect_b32 s11, s15, s21
	s_cselect_b32 s13, s14, s20
	s_cselect_b32 s19, s17, s23
	s_cselect_b32 s38, s16, s22
	s_add_u32 s20, s20, 0x40080
	s_addc_u32 s21, s21, 0
	s_add_u32 s39, s22, 0x100
	v_mov_b32_e32 v2, 0
	s_addc_u32 s56, s23, 0
	s_mov_b32 s22, 0
	v_mov_b32_e32 v3, v2
	v_mov_b32_e32 v4, v2
	v_mov_b32_e32 v5, v2
	v_mov_b32_e32 v10, v2
	v_mov_b32_e32 v11, v2
	v_mov_b32_e32 v12, v2
	v_mov_b32_e32 v13, v2
	v_mov_b32_e32 v18, v2
	v_mov_b32_e32 v19, v2
	v_mov_b32_e32 v20, v2
	v_mov_b32_e32 v21, v2
	v_mov_b32_e32 v26, v2
	v_mov_b32_e32 v27, v2
	v_mov_b32_e32 v28, v2
	v_mov_b32_e32 v29, v2
	v_mov_b32_e32 v42, v2
	v_mov_b32_e32 v43, v2
	v_mov_b32_e32 v44, v2
	v_mov_b32_e32 v45, v2
	v_mov_b32_e32 v50, v2
	v_mov_b32_e32 v51, v2
	v_mov_b32_e32 v52, v2
	v_mov_b32_e32 v53, v2
	v_mov_b32_e32 v66, v2
	v_mov_b32_e32 v67, v2
	v_mov_b32_e32 v68, v2
	v_mov_b32_e32 v69, v2
	v_mov_b32_e32 v74, v2
	v_mov_b32_e32 v75, v2
	v_mov_b32_e32 v76, v2
	v_mov_b32_e32 v77, v2
	v_mov_b32_e32 v6, v2
	v_mov_b32_e32 v7, v2
	v_mov_b32_e32 v8, v2
	v_mov_b32_e32 v9, v2
	v_mov_b32_e32 v14, v2
	v_mov_b32_e32 v15, v2
	v_mov_b32_e32 v16, v2
	v_mov_b32_e32 v17, v2
	v_mov_b32_e32 v22, v2
	v_mov_b32_e32 v23, v2
	v_mov_b32_e32 v24, v2
	v_mov_b32_e32 v25, v2
	v_mov_b32_e32 v30, v2
	v_mov_b32_e32 v31, v2
	v_mov_b32_e32 v32, v2
	v_mov_b32_e32 v33, v2
	v_mov_b32_e32 v46, v2
	v_mov_b32_e32 v47, v2
	v_mov_b32_e32 v48, v2
	v_mov_b32_e32 v49, v2
	v_mov_b32_e32 v54, v2
	v_mov_b32_e32 v55, v2
	v_mov_b32_e32 v56, v2
	v_mov_b32_e32 v57, v2
	v_mov_b32_e32 v70, v2
	v_mov_b32_e32 v71, v2
	v_mov_b32_e32 v72, v2
	v_mov_b32_e32 v73, v2
	v_mov_b32_e32 v78, v2
	v_mov_b32_e32 v79, v2
	v_mov_b32_e32 v80, v2
	v_mov_b32_e32 v81, v2
	v_mov_b32_e32 v82, v2
	v_mov_b32_e32 v83, v2
	v_mov_b32_e32 v84, v2
	v_mov_b32_e32 v85, v2
	v_mov_b32_e32 v90, v2
	v_mov_b32_e32 v91, v2
	v_mov_b32_e32 v92, v2
	v_mov_b32_e32 v93, v2
	v_mov_b32_e32 v98, v2
	v_mov_b32_e32 v99, v2
	v_mov_b32_e32 v100, v2
	v_mov_b32_e32 v101, v2
	v_mov_b32_e32 v106, v2
	v_mov_b32_e32 v107, v2
	v_mov_b32_e32 v108, v2
	v_mov_b32_e32 v109, v2
	v_mov_b32_e32 v114, v2
	v_mov_b32_e32 v115, v2
	v_mov_b32_e32 v116, v2
	v_mov_b32_e32 v117, v2
	v_mov_b32_e32 v122, v2
	v_mov_b32_e32 v123, v2
	v_mov_b32_e32 v124, v2
	v_mov_b32_e32 v125, v2
	v_mov_b32_e32 v130, v2
	v_mov_b32_e32 v131, v2
	v_mov_b32_e32 v132, v2
	v_mov_b32_e32 v133, v2
	v_mov_b32_e32 v138, v2
	v_mov_b32_e32 v139, v2
	v_mov_b32_e32 v140, v2
	v_mov_b32_e32 v141, v2
	v_mov_b32_e32 v86, v2
	v_mov_b32_e32 v87, v2
	v_mov_b32_e32 v88, v2
	v_mov_b32_e32 v89, v2
	v_mov_b32_e32 v94, v2
	v_mov_b32_e32 v95, v2
	v_mov_b32_e32 v96, v2
	v_mov_b32_e32 v97, v2
	v_mov_b32_e32 v102, v2
	v_mov_b32_e32 v103, v2
	v_mov_b32_e32 v104, v2
	v_mov_b32_e32 v105, v2
	v_mov_b32_e32 v110, v2
	v_mov_b32_e32 v111, v2
	v_mov_b32_e32 v112, v2
	v_mov_b32_e32 v113, v2
	v_mov_b32_e32 v118, v2
	v_mov_b32_e32 v119, v2
	v_mov_b32_e32 v120, v2
	v_mov_b32_e32 v121, v2
	v_mov_b32_e32 v126, v2
	v_mov_b32_e32 v127, v2
	v_mov_b32_e32 v128, v2
	v_mov_b32_e32 v129, v2
	v_mov_b32_e32 v134, v2
	v_mov_b32_e32 v135, v2
	v_mov_b32_e32 v136, v2
	v_mov_b32_e32 v137, v2
	v_mov_b32_e32 v142, v2
	v_mov_b32_e32 v143, v2
	v_mov_b32_e32 v144, v2
	v_mov_b32_e32 v145, v2

.Lzt_18:
	v_mov_b32_e32 v140, v141
	v_mov_b32_e32 v139, v141
	v_mov_b32_e32 v138, v141
	v_mov_b32_e32 v145, v141
	v_mov_b32_e32 v144, v141
	v_mov_b32_e32 v143, v141
	v_mov_b32_e32 v142, v141
	v_mov_b32_e32 v129, v141
	v_mov_b32_e32 v128, v141
	v_mov_b32_e32 v127, v141
	v_mov_b32_e32 v126, v141
	v_mov_b32_e32 v125, v141
	v_mov_b32_e32 v124, v141
	v_mov_b32_e32 v123, v141
	v_mov_b32_e32 v122, v141
	v_mov_b32_e32 v113, v141
	v_mov_b32_e32 v112, v141
	v_mov_b32_e32 v111, v141
	v_mov_b32_e32 v110, v141
	v_mov_b32_e32 v109, v141
	v_mov_b32_e32 v108, v141
	v_mov_b32_e32 v107, v141
	v_mov_b32_e32 v106, v141
	v_mov_b32_e32 v89, v141
	v_mov_b32_e32 v88, v141
	v_mov_b32_e32 v87, v141
	v_mov_b32_e32 v86, v141
	v_mov_b32_e32 v85, v141
	v_mov_b32_e32 v84, v141
	v_mov_b32_e32 v83, v141
	v_mov_b32_e32 v82, v141
	v_mov_b32_e32 v137, v141
	v_mov_b32_e32 v136, v141
	v_mov_b32_e32 v135, v141
	v_mov_b32_e32 v134, v141
	v_mov_b32_e32 v133, v141
	v_mov_b32_e32 v132, v141
	v_mov_b32_e32 v131, v141
	v_mov_b32_e32 v130, v141
	v_mov_b32_e32 v121, v141
	v_mov_b32_e32 v120, v141
	v_mov_b32_e32 v119, v141
	v_mov_b32_e32 v118, v141
	v_mov_b32_e32 v117, v141
	v_mov_b32_e32 v116, v141
	v_mov_b32_e32 v115, v141
	v_mov_b32_e32 v114, v141
	v_mov_b32_e32 v105, v141
	v_mov_b32_e32 v104, v141
	v_mov_b32_e32 v103, v141
	v_mov_b32_e32 v102, v141
	v_mov_b32_e32 v101, v141
	v_mov_b32_e32 v100, v141
	v_mov_b32_e32 v99, v141
	v_mov_b32_e32 v98, v141
	v_mov_b32_e32 v81, v141
	v_mov_b32_e32 v80, v141
	v_mov_b32_e32 v79, v141
	v_mov_b32_e32 v78, v141
	v_mov_b32_e32 v77, v141
	v_mov_b32_e32 v76, v141
	v_mov_b32_e32 v75, v141
	v_mov_b32_e32 v74, v141
	v_mov_b32_e32 v65, v141
	v_mov_b32_e32 v64, v141
	v_mov_b32_e32 v63, v141
	v_mov_b32_e32 v62, v141
	v_mov_b32_e32 v61, v141
	v_mov_b32_e32 v60, v141
	v_mov_b32_e32 v59, v141
	v_mov_b32_e32 v58, v141
	v_mov_b32_e32 v49, v141
	v_mov_b32_e32 v48, v141
	v_mov_b32_e32 v47, v141
	v_mov_b32_e32 v46, v141
	v_mov_b32_e32 v45, v141
	v_mov_b32_e32 v44, v141
	v_mov_b32_e32 v43, v141
	v_mov_b32_e32 v42, v141
	v_mov_b32_e32 v33, v141
	v_mov_b32_e32 v32, v141
	v_mov_b32_e32 v31, v141
	v_mov_b32_e32 v30, v141
	v_mov_b32_e32 v29, v141
	v_mov_b32_e32 v28, v141
	v_mov_b32_e32 v27, v141
	v_mov_b32_e32 v26, v141
	v_mov_b32_e32 v17, v141
	v_mov_b32_e32 v16, v141
	v_mov_b32_e32 v15, v141
	v_mov_b32_e32 v14, v141
	v_mov_b32_e32 v13, v141
	v_mov_b32_e32 v12, v141
	v_mov_b32_e32 v11, v141
	v_mov_b32_e32 v10, v141
	v_mov_b32_e32 v57, v141
	v_mov_b32_e32 v56, v141
	v_mov_b32_e32 v55, v141
	v_mov_b32_e32 v54, v141
	v_mov_b32_e32 v53, v141
	v_mov_b32_e32 v52, v141
	v_mov_b32_e32 v51, v141
	v_mov_b32_e32 v50, v141
	v_mov_b32_e32 v41, v141
	v_mov_b32_e32 v40, v141
	v_mov_b32_e32 v39, v141
	v_mov_b32_e32 v38, v141
	v_mov_b32_e32 v37, v141
	v_mov_b32_e32 v36, v141
	v_mov_b32_e32 v35, v141
	v_mov_b32_e32 v34, v141
	v_mov_b32_e32 v25, v141
	v_mov_b32_e32 v24, v141
	v_mov_b32_e32 v23, v141
	v_mov_b32_e32 v22, v141
	v_mov_b32_e32 v21, v141
	v_mov_b32_e32 v20, v141
	v_mov_b32_e32 v19, v141
	v_mov_b32_e32 v18, v141
	v_mov_b32_e32 v9, v141
	v_mov_b32_e32 v8, v141
	v_mov_b32_e32 v7, v141
	v_mov_b32_e32 v6, v141
	v_mov_b32_e32 v5, v141
	v_mov_b32_e32 v4, v141
	v_mov_b32_e32 v3, v141
	v_mov_b32_e32 v2, v141
	s_branch .LBB0_593

.LBB0_590:
	v_mov_b32_e32 v141, 0
	s_andn2_b64 vcc, exec, s[8:9]
	s_waitcnt vmcnt(0)
	s_waitcnt lgkmcnt(0)
	s_cbranch_vccnz .Lzt_18
	s_add_u32 s49, s10, 0x100
	s_addc_u32 s50, s11, 0
	s_add_u32 s10, s12, 0xc000
	v_mov_b32_e32 v2, 0
	s_addc_u32 s11, s13, 0
	s_mov_b32 s12, 0
	v_mov_b32_e32 v3, v2
	v_mov_b32_e32 v4, v2
	v_mov_b32_e32 v5, v2
	v_mov_b32_e32 v6, v2
	v_mov_b32_e32 v7, v2
	v_mov_b32_e32 v8, v2
	v_mov_b32_e32 v9, v2
	v_mov_b32_e32 v18, v2
	v_mov_b32_e32 v19, v2
	v_mov_b32_e32 v20, v2
	v_mov_b32_e32 v21, v2
	v_mov_b32_e32 v22, v2
	v_mov_b32_e32 v23, v2
	v_mov_b32_e32 v24, v2
	v_mov_b32_e32 v25, v2
	v_mov_b32_e32 v34, v2
	v_mov_b32_e32 v35, v2
	v_mov_b32_e32 v36, v2
	v_mov_b32_e32 v37, v2
	v_mov_b32_e32 v38, v2
	v_mov_b32_e32 v39, v2
	v_mov_b32_e32 v40, v2
	v_mov_b32_e32 v41, v2
	v_mov_b32_e32 v50, v2
	v_mov_b32_e32 v51, v2
	v_mov_b32_e32 v52, v2
	v_mov_b32_e32 v53, v2
	v_mov_b32_e32 v54, v2
	v_mov_b32_e32 v55, v2
	v_mov_b32_e32 v56, v2
	v_mov_b32_e32 v57, v2
	v_mov_b32_e32 v10, v2
	v_mov_b32_e32 v11, v2
	v_mov_b32_e32 v12, v2
	v_mov_b32_e32 v13, v2
	v_mov_b32_e32 v14, v2
	v_mov_b32_e32 v15, v2
	v_mov_b32_e32 v16, v2
	v_mov_b32_e32 v17, v2
	v_mov_b32_e32 v26, v2
	v_mov_b32_e32 v27, v2
	v_mov_b32_e32 v28, v2
	v_mov_b32_e32 v29, v2
	v_mov_b32_e32 v30, v2
	v_mov_b32_e32 v31, v2
	v_mov_b32_e32 v32, v2
	v_mov_b32_e32 v33, v2
	v_mov_b32_e32 v42, v2
	v_mov_b32_e32 v43, v2
	v_mov_b32_e32 v44, v2
	v_mov_b32_e32 v45, v2
	v_mov_b32_e32 v46, v2
	v_mov_b32_e32 v47, v2
	v_mov_b32_e32 v48, v2
	v_mov_b32_e32 v49, v2
	v_mov_b32_e32 v58, v2
	v_mov_b32_e32 v59, v2
	v_mov_b32_e32 v60, v2
	v_mov_b32_e32 v61, v2
	v_mov_b32_e32 v62, v2
	v_mov_b32_e32 v63, v2
	v_mov_b32_e32 v64, v2
	v_mov_b32_e32 v65, v2
	v_mov_b32_e32 v74, v2
	v_mov_b32_e32 v75, v2
	v_mov_b32_e32 v76, v2
	v_mov_b32_e32 v77, v2
	v_mov_b32_e32 v78, v2
	v_mov_b32_e32 v79, v2
	v_mov_b32_e32 v80, v2
	v_mov_b32_e32 v81, v2
	v_mov_b32_e32 v98, v2
	v_mov_b32_e32 v99, v2
	v_mov_b32_e32 v100, v2
	v_mov_b32_e32 v101, v2
	v_mov_b32_e32 v102, v2
	v_mov_b32_e32 v103, v2
	v_mov_b32_e32 v104, v2
	v_mov_b32_e32 v105, v2
	v_mov_b32_e32 v114, v2
	v_mov_b32_e32 v115, v2
	v_mov_b32_e32 v116, v2
	v_mov_b32_e32 v117, v2
	v_mov_b32_e32 v118, v2
	v_mov_b32_e32 v119, v2
	v_mov_b32_e32 v120, v2
	v_mov_b32_e32 v121, v2
	v_mov_b32_e32 v130, v2
	v_mov_b32_e32 v131, v2
	v_mov_b32_e32 v132, v2
	v_mov_b32_e32 v133, v2
	v_mov_b32_e32 v134, v2
	v_mov_b32_e32 v135, v2
	v_mov_b32_e32 v136, v2
	v_mov_b32_e32 v137, v2
	v_mov_b32_e32 v82, v2
	v_mov_b32_e32 v83, v2
	v_mov_b32_e32 v84, v2
	v_mov_b32_e32 v85, v2
	v_mov_b32_e32 v86, v2
	v_mov_b32_e32 v87, v2
	v_mov_b32_e32 v88, v2
	v_mov_b32_e32 v89, v2
	v_mov_b32_e32 v106, v2
	v_mov_b32_e32 v107, v2
	v_mov_b32_e32 v108, v2
	v_mov_b32_e32 v109, v2
	v_mov_b32_e32 v110, v2
	v_mov_b32_e32 v111, v2
	v_mov_b32_e32 v112, v2
	v_mov_b32_e32 v113, v2
	v_mov_b32_e32 v122, v2
	v_mov_b32_e32 v123, v2
	v_mov_b32_e32 v124, v2
	v_mov_b32_e32 v125, v2
	v_mov_b32_e32 v126, v2
	v_mov_b32_e32 v127, v2
	v_mov_b32_e32 v128, v2
	v_mov_b32_e32 v129, v2
	v_mov_b32_e32 v142, v2
	v_mov_b32_e32 v143, v2
	v_mov_b32_e32 v144, v2
	v_mov_b32_e32 v145, v2
	v_mov_b32_e32 v138, v2
	v_mov_b32_e32 v139, v2
	v_mov_b32_e32 v140, v2
	v_mov_b32_e32 v141, v2

.Lzt_24:
	v_mov_b32_e32 v144, v145
	v_mov_b32_e32 v143, v145
	v_mov_b32_e32 v142, v145
	v_mov_b32_e32 v137, v145
	v_mov_b32_e32 v136, v145
	v_mov_b32_e32 v135, v145
	v_mov_b32_e32 v134, v145
	v_mov_b32_e32 v129, v145
	v_mov_b32_e32 v128, v145
	v_mov_b32_e32 v127, v145
	v_mov_b32_e32 v126, v145
	v_mov_b32_e32 v121, v145
	v_mov_b32_e32 v120, v145
	v_mov_b32_e32 v119, v145
	v_mov_b32_e32 v118, v145
	v_mov_b32_e32 v113, v145
	v_mov_b32_e32 v112, v145
	v_mov_b32_e32 v111, v145
	v_mov_b32_e32 v110, v145
	v_mov_b32_e32 v105, v145
	v_mov_b32_e32 v104, v145
	v_mov_b32_e32 v103, v145
	v_mov_b32_e32 v102, v145
	v_mov_b32_e32 v97, v145
	v_mov_b32_e32 v96, v145
	v_mov_b32_e32 v95, v145
	v_mov_b32_e32 v94, v145
	v_mov_b32_e32 v89, v145
	v_mov_b32_e32 v88, v145
	v_mov_b32_e32 v87, v145
	v_mov_b32_e32 v86, v145
	v_mov_b32_e32 v141, v145
	v_mov_b32_e32 v140, v145
	v_mov_b32_e32 v139, v145
	v_mov_b32_e32 v138, v145
	v_mov_b32_e32 v133, v145
	v_mov_b32_e32 v132, v145
	v_mov_b32_e32 v131, v145
	v_mov_b32_e32 v130, v145
	v_mov_b32_e32 v125, v145
	v_mov_b32_e32 v124, v145
	v_mov_b32_e32 v123, v145
	v_mov_b32_e32 v122, v145
	v_mov_b32_e32 v117, v145
	v_mov_b32_e32 v116, v145
	v_mov_b32_e32 v115, v145
	v_mov_b32_e32 v114, v145
	v_mov_b32_e32 v109, v145
	v_mov_b32_e32 v108, v145
	v_mov_b32_e32 v107, v145
	v_mov_b32_e32 v106, v145
	v_mov_b32_e32 v101, v145
	v_mov_b32_e32 v100, v145
	v_mov_b32_e32 v99, v145
	v_mov_b32_e32 v98, v145
	v_mov_b32_e32 v93, v145
	v_mov_b32_e32 v92, v145
	v_mov_b32_e32 v91, v145
	v_mov_b32_e32 v90, v145
	v_mov_b32_e32 v85, v145
	v_mov_b32_e32 v84, v145
	v_mov_b32_e32 v83, v145
	v_mov_b32_e32 v82, v145
	v_mov_b32_e32 v81, v145
	v_mov_b32_e32 v80, v145
	v_mov_b32_e32 v79, v145
	v_mov_b32_e32 v78, v145
	v_mov_b32_e32 v73, v145
	v_mov_b32_e32 v72, v145
	v_mov_b32_e32 v71, v145
	v_mov_b32_e32 v70, v145
	v_mov_b32_e32 v65, v145
	v_mov_b32_e32 v64, v145
	v_mov_b32_e32 v63, v145
	v_mov_b32_e32 v62, v145
	v_mov_b32_e32 v57, v145
	v_mov_b32_e32 v56, v145
	v_mov_b32_e32 v55, v145
	v_mov_b32_e32 v54, v145
	v_mov_b32_e32 v41, v145
	v_mov_b32_e32 v40, v145
	v_mov_b32_e32 v39, v145
	v_mov_b32_e32 v38, v145
	v_mov_b32_e32 v29, v145
	v_mov_b32_e32 v28, v145
	v_mov_b32_e32 v27, v145
	v_mov_b32_e32 v26, v145
	v_mov_b32_e32 v17, v145
	v_mov_b32_e32 v16, v145
	v_mov_b32_e32 v15, v145
	v_mov_b32_e32 v14, v145
	v_mov_b32_e32 v9, v145
	v_mov_b32_e32 v8, v145
	v_mov_b32_e32 v7, v145
	v_mov_b32_e32 v6, v145
	v_mov_b32_e32 v77, v145
	v_mov_b32_e32 v76, v145
	v_mov_b32_e32 v75, v145
	v_mov_b32_e32 v74, v145
	v_mov_b32_e32 v69, v145
	v_mov_b32_e32 v68, v145
	v_mov_b32_e32 v67, v145
	v_mov_b32_e32 v66, v145
	v_mov_b32_e32 v61, v145
	v_mov_b32_e32 v60, v145
	v_mov_b32_e32 v59, v145
	v_mov_b32_e32 v58, v145
	v_mov_b32_e32 v53, v145
	v_mov_b32_e32 v52, v145
	v_mov_b32_e32 v51, v145
	v_mov_b32_e32 v50, v145
	v_mov_b32_e32 v33, v145
	v_mov_b32_e32 v32, v145
	v_mov_b32_e32 v31, v145
	v_mov_b32_e32 v30, v145
	v_mov_b32_e32 v21, v145
	v_mov_b32_e32 v20, v145
	v_mov_b32_e32 v19, v145
	v_mov_b32_e32 v18, v145
	v_mov_b32_e32 v13, v145
	v_mov_b32_e32 v12, v145
	v_mov_b32_e32 v11, v145
	v_mov_b32_e32 v10, v145
	v_mov_b32_e32 v5, v145
	v_mov_b32_e32 v4, v145
	v_mov_b32_e32 v3, v145
	v_mov_b32_e32 v2, v145
	s_branch .LBB0_800

.LBB0_797:
	s_ashr_i32 s15, s14, 31
	s_lshl_b64 s[16:17], s[14:15], 19
	s_add_u32 s16, s64, s16
	s_addc_u32 s17, s65, s17
	s_ashr_i32 s13, s12, 31
	s_lshl_b64 s[18:19], s[12:13], 19
	s_add_u32 s18, s31, s18
	v_mov_b32_e32 v145, 0
	s_addc_u32 s19, s34, s19
	s_andn2_b64 vcc, exec, s[8:9]
	s_waitcnt vmcnt(0)
	s_cbranch_vccnz .Lzt_24
	v_mov_b64_e32 v[2:3], 0x600
	v_cmp_lt_i64_e32 vcc, s[28:29], v[2:3]
	s_and_b64 s[28:29], vcc, exec
	s_cselect_b32 s13, s17, s25
	s_cselect_b32 s15, s16, s24
	s_cselect_b32 s21, s19, s27
	s_cselect_b32 s39, s18, s26
	s_add_u32 s24, s24, 0x40080
	s_addc_u32 s25, s25, 0
	s_add_u32 s55, s26, 0x100
	v_mov_b32_e32 v2, 0
	s_addc_u32 s56, s27, 0
	s_mov_b32 s26, 0
	v_mov_b32_e32 v3, v2
	v_mov_b32_e32 v4, v2
	v_mov_b32_e32 v5, v2
	v_mov_b32_e32 v10, v2
	v_mov_b32_e32 v11, v2
	v_mov_b32_e32 v12, v2
	v_mov_b32_e32 v13, v2
	v_mov_b32_e32 v18, v2
	v_mov_b32_e32 v19, v2
	v_mov_b32_e32 v20, v2
	v_mov_b32_e32 v21, v2
	v_mov_b32_e32 v30, v2
	v_mov_b32_e32 v31, v2
	v_mov_b32_e32 v32, v2
	v_mov_b32_e32 v33, v2
	v_mov_b32_e32 v50, v2
	v_mov_b32_e32 v51, v2
	v_mov_b32_e32 v52, v2
	v_mov_b32_e32 v53, v2
	v_mov_b32_e32 v58, v2
	v_mov_b32_e32 v59, v2
	v_mov_b32_e32 v60, v2
	v_mov_b32_e32 v61, v2
	v_mov_b32_e32 v66, v2
	v_mov_b32_e32 v67, v2
	v_mov_b32_e32 v68, v2
	v_mov_b32_e32 v69, v2
	v_mov_b32_e32 v74, v2
	v_mov_b32_e32 v75, v2
	v_mov_b32_e32 v76, v2
	v_mov_b32_e32 v77, v2
	v_mov_b32_e32 v6, v2
	v_mov_b32_e32 v7, v2
	v_mov_b32_e32 v8, v2
	v_mov_b32_e32 v9, v2
	v_mov_b32_e32 v14, v2
	v_mov_b32_e32 v15, v2
	v_mov_b32_e32 v16, v2
	v_mov_b32_e32 v17, v2
	v_mov_b32_e32 v26, v2
	v_mov_b32_e32 v27, v2
	v_mov_b32_e32 v28, v2
	v_mov_b32_e32 v29, v2
	v_mov_b32_e32 v38, v2
	v_mov_b32_e32 v39, v2
	v_mov_b32_e32 v40, v2
	v_mov_b32_e32 v41, v2
	v_mov_b32_e32 v54, v2
	v_mov_b32_e32 v55, v2
	v_mov_b32_e32 v56, v2
	v_mov_b32_e32 v57, v2
	v_mov_b32_e32 v62, v2
	v_mov_b32_e32 v63, v2
	v_mov_b32_e32 v64, v2
	v_mov_b32_e32 v65, v2
	v_mov_b32_e32 v70, v2
	v_mov_b32_e32 v71, v2
	v_mov_b32_e32 v72, v2
	v_mov_b32_e32 v73, v2
	v_mov_b32_e32 v78, v2
	v_mov_b32_e32 v79, v2
	v_mov_b32_e32 v80, v2
	v_mov_b32_e32 v81, v2
	v_mov_b32_e32 v82, v2
	v_mov_b32_e32 v83, v2
	v_mov_b32_e32 v84, v2
	v_mov_b32_e32 v85, v2
	v_mov_b32_e32 v90, v2
	v_mov_b32_e32 v91, v2
	v_mov_b32_e32 v92, v2
	v_mov_b32_e32 v93, v2
	v_mov_b32_e32 v98, v2
	v_mov_b32_e32 v99, v2
	v_mov_b32_e32 v100, v2
	v_mov_b32_e32 v101, v2
	v_mov_b32_e32 v106, v2
	v_mov_b32_e32 v107, v2
	v_mov_b32_e32 v108, v2
	v_mov_b32_e32 v109, v2
	v_mov_b32_e32 v114, v2
	v_mov_b32_e32 v115, v2
	v_mov_b32_e32 v116, v2
	v_mov_b32_e32 v117, v2
	v_mov_b32_e32 v122, v2
	v_mov_b32_e32 v123, v2
	v_mov_b32_e32 v124, v2
	v_mov_b32_e32 v125, v2
	v_mov_b32_e32 v130, v2
	v_mov_b32_e32 v131, v2
	v_mov_b32_e32 v132, v2
	v_mov_b32_e32 v133, v2
	v_mov_b32_e32 v138, v2
	v_mov_b32_e32 v139, v2
	v_mov_b32_e32 v140, v2
	v_mov_b32_e32 v141, v2
	v_mov_b32_e32 v86, v2
	v_mov_b32_e32 v87, v2
	v_mov_b32_e32 v88, v2
	v_mov_b32_e32 v89, v2
	v_mov_b32_e32 v94, v2
	v_mov_b32_e32 v95, v2
	v_mov_b32_e32 v96, v2
	v_mov_b32_e32 v97, v2
	v_mov_b32_e32 v102, v2
	v_mov_b32_e32 v103, v2
	v_mov_b32_e32 v104, v2
	v_mov_b32_e32 v105, v2
	v_mov_b32_e32 v110, v2
	v_mov_b32_e32 v111, v2
	v_mov_b32_e32 v112, v2
	v_mov_b32_e32 v113, v2
	v_mov_b32_e32 v118, v2
	v_mov_b32_e32 v119, v2
	v_mov_b32_e32 v120, v2
	v_mov_b32_e32 v121, v2
	v_mov_b32_e32 v126, v2
	v_mov_b32_e32 v127, v2
	v_mov_b32_e32 v128, v2
	v_mov_b32_e32 v129, v2
	v_mov_b32_e32 v134, v2
	v_mov_b32_e32 v135, v2
	v_mov_b32_e32 v136, v2
	v_mov_b32_e32 v137, v2
	v_mov_b32_e32 v142, v2
	v_mov_b32_e32 v143, v2
	v_mov_b32_e32 v144, v2
	v_mov_b32_e32 v145, v2

.Lzt_26:
	v_mov_b32_e32 v136, v137
	v_mov_b32_e32 v135, v137
	v_mov_b32_e32 v134, v137
	v_mov_b32_e32 v125, v137
	v_mov_b32_e32 v124, v137
	v_mov_b32_e32 v123, v137
	v_mov_b32_e32 v122, v137
	v_mov_b32_e32 v113, v137
	v_mov_b32_e32 v112, v137
	v_mov_b32_e32 v111, v137
	v_mov_b32_e32 v110, v137
	v_mov_b32_e32 v109, v137
	v_mov_b32_e32 v108, v137
	v_mov_b32_e32 v107, v137
	v_mov_b32_e32 v106, v137
	v_mov_b32_e32 v97, v137
	v_mov_b32_e32 v96, v137
	v_mov_b32_e32 v95, v137
	v_mov_b32_e32 v94, v137
	v_mov_b32_e32 v93, v137
	v_mov_b32_e32 v92, v137
	v_mov_b32_e32 v91, v137
	v_mov_b32_e32 v90, v137
	v_mov_b32_e32 v81, v137
	v_mov_b32_e32 v80, v137
	v_mov_b32_e32 v79, v137
	v_mov_b32_e32 v78, v137
	v_mov_b32_e32 v77, v137
	v_mov_b32_e32 v76, v137
	v_mov_b32_e32 v75, v137
	v_mov_b32_e32 v74, v137
	v_mov_b32_e32 v121, v137
	v_mov_b32_e32 v120, v137
	v_mov_b32_e32 v119, v137
	v_mov_b32_e32 v118, v137
	v_mov_b32_e32 v117, v137
	v_mov_b32_e32 v116, v137
	v_mov_b32_e32 v115, v137
	v_mov_b32_e32 v114, v137
	v_mov_b32_e32 v105, v137
	v_mov_b32_e32 v104, v137
	v_mov_b32_e32 v103, v137
	v_mov_b32_e32 v102, v137
	v_mov_b32_e32 v101, v137
	v_mov_b32_e32 v100, v137
	v_mov_b32_e32 v99, v137
	v_mov_b32_e32 v98, v137
	v_mov_b32_e32 v89, v137
	v_mov_b32_e32 v88, v137
	v_mov_b32_e32 v87, v137
	v_mov_b32_e32 v86, v137
	v_mov_b32_e32 v85, v137
	v_mov_b32_e32 v84, v137
	v_mov_b32_e32 v83, v137
	v_mov_b32_e32 v82, v137
	v_mov_b32_e32 v73, v137
	v_mov_b32_e32 v72, v137
	v_mov_b32_e32 v71, v137
	v_mov_b32_e32 v70, v137
	v_mov_b32_e32 v69, v137
	v_mov_b32_e32 v68, v137
	v_mov_b32_e32 v67, v137
	v_mov_b32_e32 v66, v137
	v_mov_b32_e32 v65, v137
	v_mov_b32_e32 v64, v137
	v_mov_b32_e32 v63, v137
	v_mov_b32_e32 v62, v137
	v_mov_b32_e32 v61, v137
	v_mov_b32_e32 v60, v137
	v_mov_b32_e32 v59, v137
	v_mov_b32_e32 v58, v137
	v_mov_b32_e32 v49, v137
	v_mov_b32_e32 v48, v137
	v_mov_b32_e32 v47, v137
	v_mov_b32_e32 v46, v137
	v_mov_b32_e32 v45, v137
	v_mov_b32_e32 v44, v137
	v_mov_b32_e32 v43, v137
	v_mov_b32_e32 v42, v137
	v_mov_b32_e32 v33, v137
	v_mov_b32_e32 v32, v137
	v_mov_b32_e32 v31, v137
	v_mov_b32_e32 v30, v137
	v_mov_b32_e32 v29, v137
	v_mov_b32_e32 v28, v137
	v_mov_b32_e32 v27, v137
	v_mov_b32_e32 v26, v137
	v_mov_b32_e32 v17, v137
	v_mov_b32_e32 v16, v137
	v_mov_b32_e32 v15, v137
	v_mov_b32_e32 v14, v137
	v_mov_b32_e32 v13, v137
	v_mov_b32_e32 v12, v137
	v_mov_b32_e32 v11, v137
	v_mov_b32_e32 v10, v137
	v_mov_b32_e32 v57, v137
	v_mov_b32_e32 v56, v137
	v_mov_b32_e32 v55, v137
	v_mov_b32_e32 v54, v137
	v_mov_b32_e32 v53, v137
	v_mov_b32_e32 v52, v137
	v_mov_b32_e32 v51, v137
	v_mov_b32_e32 v50, v137
	v_mov_b32_e32 v41, v137
	v_mov_b32_e32 v40, v137
	v_mov_b32_e32 v39, v137
	v_mov_b32_e32 v38, v137
	v_mov_b32_e32 v37, v137
	v_mov_b32_e32 v36, v137
	v_mov_b32_e32 v35, v137
	v_mov_b32_e32 v34, v137
	v_mov_b32_e32 v25, v137
	v_mov_b32_e32 v24, v137
	v_mov_b32_e32 v23, v137
	v_mov_b32_e32 v22, v137
	v_mov_b32_e32 v21, v137
	v_mov_b32_e32 v20, v137
	v_mov_b32_e32 v19, v137
	v_mov_b32_e32 v18, v137
	v_mov_b32_e32 v9, v137
	v_mov_b32_e32 v8, v137
	v_mov_b32_e32 v7, v137
	v_mov_b32_e32 v6, v137
	v_mov_b32_e32 v5, v137
	v_mov_b32_e32 v4, v137
	v_mov_b32_e32 v3, v137
	v_mov_b32_e32 v2, v137
	s_branch .LBB0_845

.LBB0_842:
	v_mov_b32_e32 v137, 0
	s_andn2_b64 vcc, exec, s[10:11]
	s_waitcnt vmcnt(0)
	s_waitcnt lgkmcnt(0)
	s_cbranch_vccnz .Lzt_26
	s_add_u32 s51, s12, 0x100
	s_addc_u32 s52, s13, 0
	s_add_u32 s12, s14, 0xc000
	v_mov_b32_e32 v2, 0
	s_addc_u32 s13, s15, 0
	s_mov_b32 s14, 0
	v_mov_b32_e32 v3, v2
	v_mov_b32_e32 v4, v2
	v_mov_b32_e32 v5, v2
	v_mov_b32_e32 v6, v2
	v_mov_b32_e32 v7, v2
	v_mov_b32_e32 v8, v2
	v_mov_b32_e32 v9, v2
	v_mov_b32_e32 v18, v2
	v_mov_b32_e32 v19, v2
	v_mov_b32_e32 v20, v2
	v_mov_b32_e32 v21, v2
	v_mov_b32_e32 v22, v2
	v_mov_b32_e32 v23, v2
	v_mov_b32_e32 v24, v2
	v_mov_b32_e32 v25, v2
	v_mov_b32_e32 v34, v2
	v_mov_b32_e32 v35, v2
	v_mov_b32_e32 v36, v2
	v_mov_b32_e32 v37, v2
	v_mov_b32_e32 v38, v2
	v_mov_b32_e32 v39, v2
	v_mov_b32_e32 v40, v2
	v_mov_b32_e32 v41, v2
	v_mov_b32_e32 v50, v2
	v_mov_b32_e32 v51, v2
	v_mov_b32_e32 v52, v2
	v_mov_b32_e32 v53, v2
	v_mov_b32_e32 v54, v2
	v_mov_b32_e32 v55, v2
	v_mov_b32_e32 v56, v2
	v_mov_b32_e32 v57, v2
	v_mov_b32_e32 v10, v2
	v_mov_b32_e32 v11, v2
	v_mov_b32_e32 v12, v2
	v_mov_b32_e32 v13, v2
	v_mov_b32_e32 v14, v2
	v_mov_b32_e32 v15, v2
	v_mov_b32_e32 v16, v2
	v_mov_b32_e32 v17, v2
	v_mov_b32_e32 v26, v2
	v_mov_b32_e32 v27, v2
	v_mov_b32_e32 v28, v2
	v_mov_b32_e32 v29, v2
	v_mov_b32_e32 v30, v2
	v_mov_b32_e32 v31, v2
	v_mov_b32_e32 v32, v2
	v_mov_b32_e32 v33, v2
	v_mov_b32_e32 v42, v2
	v_mov_b32_e32 v43, v2
	v_mov_b32_e32 v44, v2
	v_mov_b32_e32 v45, v2
	v_mov_b32_e32 v46, v2
	v_mov_b32_e32 v47, v2
	v_mov_b32_e32 v48, v2
	v_mov_b32_e32 v49, v2
	v_mov_b32_e32 v58, v2
	v_mov_b32_e32 v59, v2
	v_mov_b32_e32 v60, v2
	v_mov_b32_e32 v61, v2
	v_mov_b32_e32 v62, v2
	v_mov_b32_e32 v63, v2
	v_mov_b32_e32 v64, v2
	v_mov_b32_e32 v65, v2
	v_mov_b32_e32 v66, v2
	v_mov_b32_e32 v67, v2
	v_mov_b32_e32 v68, v2
	v_mov_b32_e32 v69, v2
	v_mov_b32_e32 v70, v2
	v_mov_b32_e32 v71, v2
	v_mov_b32_e32 v72, v2
	v_mov_b32_e32 v73, v2
	v_mov_b32_e32 v82, v2
	v_mov_b32_e32 v83, v2
	v_mov_b32_e32 v84, v2
	v_mov_b32_e32 v85, v2
	v_mov_b32_e32 v86, v2
	v_mov_b32_e32 v87, v2
	v_mov_b32_e32 v88, v2
	v_mov_b32_e32 v89, v2
	v_mov_b32_e32 v98, v2
	v_mov_b32_e32 v99, v2
	v_mov_b32_e32 v100, v2
	v_mov_b32_e32 v101, v2
	v_mov_b32_e32 v102, v2
	v_mov_b32_e32 v103, v2
	v_mov_b32_e32 v104, v2
	v_mov_b32_e32 v105, v2
	v_mov_b32_e32 v114, v2
	v_mov_b32_e32 v115, v2
	v_mov_b32_e32 v116, v2
	v_mov_b32_e32 v117, v2
	v_mov_b32_e32 v118, v2
	v_mov_b32_e32 v119, v2
	v_mov_b32_e32 v120, v2
	v_mov_b32_e32 v121, v2
	v_mov_b32_e32 v74, v2
	v_mov_b32_e32 v75, v2
	v_mov_b32_e32 v76, v2
	v_mov_b32_e32 v77, v2
	v_mov_b32_e32 v78, v2
	v_mov_b32_e32 v79, v2
	v_mov_b32_e32 v80, v2
	v_mov_b32_e32 v81, v2
	v_mov_b32_e32 v90, v2
	v_mov_b32_e32 v91, v2
	v_mov_b32_e32 v92, v2
	v_mov_b32_e32 v93, v2
	v_mov_b32_e32 v94, v2
	v_mov_b32_e32 v95, v2
	v_mov_b32_e32 v96, v2
	v_mov_b32_e32 v97, v2
	v_mov_b32_e32 v106, v2
	v_mov_b32_e32 v107, v2
	v_mov_b32_e32 v108, v2
	v_mov_b32_e32 v109, v2
	v_mov_b32_e32 v110, v2
	v_mov_b32_e32 v111, v2
	v_mov_b32_e32 v112, v2
	v_mov_b32_e32 v113, v2
	v_mov_b32_e32 v122, v2
	v_mov_b32_e32 v123, v2
	v_mov_b32_e32 v124, v2
	v_mov_b32_e32 v125, v2
	v_mov_b32_e32 v134, v2
	v_mov_b32_e32 v135, v2
	v_mov_b32_e32 v136, v2
	v_mov_b32_e32 v137, v2

.LBB0_872:
	s_ashr_i32 s5, s4, 31
	s_lshl_b64 s[6:7], s[4:5], 19
	s_add_u32 s6, s64, s6
	s_addc_u32 s7, s65, s7
	s_ashr_i32 s3, s2, 31
	s_lshl_b64 s[8:9], s[2:3], 19
	s_add_u32 s8, s66, s8
	v_mov_b32_e32 v141, 0
	s_addc_u32 s9, s67, s9
	s_andn2_b64 vcc, exec, s[0:1]
	s_waitcnt vmcnt(0)
	s_cbranch_vccnz .Lzt_28
	v_mov_b64_e32 v[2:3], 0xb00
	v_cmp_lt_i64_e32 vcc, s[16:17], v[2:3]
	s_and_b64 s[16:17], vcc, exec
	s_cselect_b32 s3, s7, s13
	s_cselect_b32 s5, s6, s12
	s_cselect_b32 s39, s9, s15
	s_cselect_b32 s40, s8, s14
	s_add_u32 s12, s12, 0x40080
	s_addc_u32 s13, s13, 0
	s_add_u32 s41, s14, 0x100
	v_mov_b32_e32 v2, 0
	s_addc_u32 s42, s15, 0
	s_mov_b32 s14, 0
	v_mov_b32_e32 v3, v2
	v_mov_b32_e32 v4, v2
	v_mov_b32_e32 v5, v2
	v_mov_b32_e32 v10, v2
	v_mov_b32_e32 v11, v2
	v_mov_b32_e32 v12, v2
	v_mov_b32_e32 v13, v2
	v_mov_b32_e32 v18, v2
	v_mov_b32_e32 v19, v2
	v_mov_b32_e32 v20, v2
	v_mov_b32_e32 v21, v2
	v_mov_b32_e32 v26, v2
	v_mov_b32_e32 v27, v2
	v_mov_b32_e32 v28, v2
	v_mov_b32_e32 v29, v2
	v_mov_b32_e32 v34, v2
	v_mov_b32_e32 v35, v2
	v_mov_b32_e32 v36, v2
	v_mov_b32_e32 v37, v2
	v_mov_b32_e32 v42, v2
	v_mov_b32_e32 v43, v2
	v_mov_b32_e32 v44, v2
	v_mov_b32_e32 v45, v2
	v_mov_b32_e32 v50, v2
	v_mov_b32_e32 v51, v2
	v_mov_b32_e32 v52, v2
	v_mov_b32_e32 v53, v2
	v_mov_b32_e32 v58, v2
	v_mov_b32_e32 v59, v2
	v_mov_b32_e32 v60, v2
	v_mov_b32_e32 v61, v2
	v_mov_b32_e32 v6, v2
	v_mov_b32_e32 v7, v2
	v_mov_b32_e32 v8, v2
	v_mov_b32_e32 v9, v2
	v_mov_b32_e32 v14, v2
	v_mov_b32_e32 v15, v2
	v_mov_b32_e32 v16, v2
	v_mov_b32_e32 v17, v2
	v_mov_b32_e32 v22, v2
	v_mov_b32_e32 v23, v2
	v_mov_b32_e32 v24, v2
	v_mov_b32_e32 v25, v2
	v_mov_b32_e32 v30, v2
	v_mov_b32_e32 v31, v2
	v_mov_b32_e32 v32, v2
	v_mov_b32_e32 v33, v2
	v_mov_b32_e32 v38, v2
	v_mov_b32_e32 v39, v2
	v_mov_b32_e32 v40, v2
	v_mov_b32_e32 v41, v2
	v_mov_b32_e32 v46, v2
	v_mov_b32_e32 v47, v2
	v_mov_b32_e32 v48, v2
	v_mov_b32_e32 v49, v2
	v_mov_b32_e32 v54, v2
	v_mov_b32_e32 v55, v2
	v_mov_b32_e32 v56, v2
	v_mov_b32_e32 v57, v2
	v_mov_b32_e32 v62, v2
	v_mov_b32_e32 v63, v2
	v_mov_b32_e32 v64, v2
	v_mov_b32_e32 v65, v2
	v_mov_b32_e32 v66, v2
	v_mov_b32_e32 v67, v2
	v_mov_b32_e32 v68, v2
	v_mov_b32_e32 v69, v2
	v_mov_b32_e32 v74, v2
	v_mov_b32_e32 v75, v2
	v_mov_b32_e32 v76, v2
	v_mov_b32_e32 v77, v2
	v_mov_b32_e32 v90, v2
	v_mov_b32_e32 v91, v2
	v_mov_b32_e32 v92, v2
	v_mov_b32_e32 v93, v2
	v_mov_b32_e32 v106, v2
	v_mov_b32_e32 v107, v2
	v_mov_b32_e32 v108, v2
	v_mov_b32_e32 v109, v2
	v_mov_b32_e32 v114, v2
	v_mov_b32_e32 v115, v2
	v_mov_b32_e32 v116, v2
	v_mov_b32_e32 v117, v2
	v_mov_b32_e32 v122, v2
	v_mov_b32_e32 v123, v2
	v_mov_b32_e32 v124, v2
	v_mov_b32_e32 v125, v2
	v_mov_b32_e32 v130, v2
	v_mov_b32_e32 v131, v2
	v_mov_b32_e32 v132, v2
	v_mov_b32_e32 v133, v2
	v_mov_b32_e32 v142, v2
	v_mov_b32_e32 v143, v2
	v_mov_b32_e32 v144, v2
	v_mov_b32_e32 v145, v2
	v_mov_b32_e32 v70, v2
	v_mov_b32_e32 v71, v2
	v_mov_b32_e32 v72, v2
	v_mov_b32_e32 v73, v2
	v_mov_b32_e32 v78, v2
	v_mov_b32_e32 v79, v2
	v_mov_b32_e32 v80, v2
	v_mov_b32_e32 v81, v2
	v_mov_b32_e32 v94, v2
	v_mov_b32_e32 v95, v2
	v_mov_b32_e32 v96, v2
	v_mov_b32_e32 v97, v2
	v_mov_b32_e32 v110, v2
	v_mov_b32_e32 v111, v2
	v_mov_b32_e32 v112, v2
	v_mov_b32_e32 v113, v2
	v_mov_b32_e32 v118, v2
	v_mov_b32_e32 v119, v2
	v_mov_b32_e32 v120, v2
	v_mov_b32_e32 v121, v2
	v_mov_b32_e32 v126, v2
	v_mov_b32_e32 v127, v2
	v_mov_b32_e32 v128, v2
	v_mov_b32_e32 v129, v2
	v_mov_b32_e32 v134, v2
	v_mov_b32_e32 v135, v2
	v_mov_b32_e32 v136, v2
	v_mov_b32_e32 v137, v2
	v_mov_b32_e32 v138, v2
	v_mov_b32_e32 v139, v2
	v_mov_b32_e32 v140, v2
	v_mov_b32_e32 v141, v2
